# stack: attention loop pipelined+interleaved softmax, static prio, conv0->conv1 grid barrier dropped, filter unit rebalance, conv epilogue loads batched, gemm_half read ring, norm gain/shift/scale load
# speedup vs baseline: 1.0235x; 1.0235x over previous
.LBB0_129:
	v_mov_b32_e32 v0, 0x21c90
	s_barrier
	s_lshr_b32 s100, s26, 1
	s_and_b32 s100, s100, 0x80
	s_lshl_b32 s101, s26, 1
	s_and_b32 s101, s101, 0x100
	s_or_b32 s100, s100, s101
	s_andn2_b32 s101, s26, 0x180
	s_or_b32 s100, s100, s101
	s_lshl_b32 s36, s100, 3
	v_add_u32_e32 v0, 0, v0
	s_ashr_i32 s8, s100, 8
	s_and_b32 s27, s36, 0x3f8
	s_and_b32 s33, s100, 0x80
	ds_read_b64 v[0:1], v0
	s_cmp_eq_u32 s33, 0
	s_cselect_b64 s[10:11], -1, 0
	s_and_b64 s[12:13], s[10:11], exec
	s_cselect_b32 s35, s20, 0x1000
	s_ashr_i32 s9, s8, 31
	s_waitcnt lgkmcnt(0)
	v_readfirstlane_b32 s17, v0
	s_lshl_b64 s[12:13], s[8:9], 18
	v_readfirstlane_b32 s16, v1
	s_add_u32 s12, s17, s12
	s_addc_u32 s13, s16, s13
	v_lshl_add_u64 v[0:1], s[12:13], 0, v[72:73]
	s_lshl_b32 s48, s27, 2
	v_lshl_add_u64 v[0:1], v[0:1], 0, s[48:49]
	v_lshl_add_u64 v[0:1], v[0:1], 0, v[74:75]
	global_load_dword v0, v[0:1], off
	v_mov_b32_e32 v1, 0x21ca0
	v_cmp_gt_i32_e32 vcc, s35, v66
	v_mov_b32_e32 v70, v71
	s_waitcnt vmcnt(0)
	ds_write_b32 v69, v0
	s_waitcnt lgkmcnt(0)
	s_barrier
	s_nop 0
	v_add_u32_e32 v0, 0, v1
	ds_read_b64 v[0:1], v0
	s_waitcnt lgkmcnt(0)
	v_readfirstlane_b32 s17, v1
	v_readfirstlane_b32 s16, v0
	s_and_saveexec_b64 s[12:13], vcc
	s_cbranch_execz .LBB0_133
	s_and_b32 s9, s36, 0x200
	s_lshl_b32 s37, s8, 10
	s_and_b32 s36, s36, 0x1f8
	s_or_b32 s9, s9, s37
	v_or_b32_e32 v0, s36, v68
	v_or_b32_e32 v0, s9, v0
	v_ashrrev_i32_e32 v1, 31, v0
	v_lshl_add_u64 v[0:1], v[0:1], 2, s[16:17]
	global_load_dword v2, v[0:1], off
	s_lshl_b32 s9, s100, 1
	s_lshr_b32 s40, s35, 1
	s_and_b32 s41, s9, 0x100
	s_and_b64 s[36:37], s[10:11], exec
	s_mul_i32 s39, s8, 0x1100
	s_cselect_b32 s36, 8, 12
	s_sub_i32 s9, 0, s40
	s_mul_hi_i32 s38, s8, 0x1100
	v_lshlrev_b32_e32 v0, s36, v68
	s_add_u32 s36, s41, s39
	v_cvt_f32_u32_e32 v132, s35
	s_addc_u32 s37, 0, s38
	v_lshl_add_u32 v133, v0, 2, v128
	v_lshl_add_u64 v[0:1], s[36:37], 0, v[66:67]
	v_lshlrev_b64 v[0:1], 8, v[0:1]
	v_mov_b32_e32 v70, 0
	s_mov_b64 s[16:17], 0
	v_lshl_add_u64 v[76:77], s[4:5], 0, v[0:1]
	v_mov_b32_e32 v135, v66
	s_waitcnt vmcnt(0)
	v_and_b32_e32 v134, 0x7fffffff, v2

.LBB0_167:
	s_or_b64 exec, exec, s[14:15]
	v_add_u32_e32 v31, 0xffffe000, v40
	v_lshrrev_b32_e32 v31, 12, v31
	v_add_u32_e32 v31, 1, v31
	v_cmp_lt_i32_e32 vcc, s48, v40
	v_mov_b64_e32 v[70:71], s[4:5]
	s_waitcnt vmcnt(3)
	v_mov_b32_e32 v86, v21
	v_cndmask_b32_e32 v31, 0, v31, vcc
	v_add_u32_e32 v31, s69, v31
	v_mad_u64_u32 v[74:75], s[6:7], v31, s50, v[70:71]
	v_lshl_add_u64 v[82:83], v[74:75], 0, s[58:59]
	v_lshl_add_u64 v[84:85], v[74:75], 0, v[164:165]
	v_lshl_add_u64 v[78:79], v[82:83], 0, v[164:165]
	s_nop 0
	v_mov_b32_e32 v252, v78
	v_mov_b32_e32 v253, v79
	global_load_dwordx4 v[198:201], v[28:29], off
	global_load_dwordx4 v[202:205], v[28:29], off offset:1024
	global_load_dwordx4 v[206:209], v[28:29], off offset:2048
	global_load_dwordx4 v[210:213], v[28:29], off offset:3072
	global_load_dwordx4 v[214:217], v[84:85], off
	global_load_dwordx4 v[218:221], v[84:85], off offset:1024
	global_load_dwordx4 v[222:225], v[84:85], off offset:2048
	global_load_dwordx4 v[226:229], v[84:85], off offset:3072
	global_load_dwordx4 v[230:233], v[252:253], off
	global_load_dwordx4 v[240:243], v[252:253], off offset:1024
	global_load_dwordx4 v[244:247], v[252:253], off offset:2048
	global_load_dwordx4 v[248:251], v[252:253], off offset:3072
	s_waitcnt vmcnt(0)
	v_mov_b32_e32 v70, v198
	v_mov_b32_e32 v71, v199
	v_mov_b32_e32 v72, v200
	v_mov_b32_e32 v73, v201
	v_mov_b32_e32 v74, v214
	v_mov_b32_e32 v75, v215
	v_mov_b32_e32 v76, v216
	v_mov_b32_e32 v77, v217
	v_mov_b32_e32 v78, v230
	v_mov_b32_e32 v79, v231
	v_mov_b32_e32 v80, v232
	v_mov_b32_e32 v81, v233
	v_mov_b32_e32 v87, v17
	v_mov_b32_e32 v68, v20
	v_mov_b32_e32 v69, v16
	v_pk_mul_f32 v[86:87], v[86:87], v[86:87]
	v_mov_b32_e32 v88, v22
	v_mov_b32_e32 v89, v18
	v_pk_fma_f32 v[68:69], v[68:69], v[68:69], v[86:87]
	v_mov_b32_e32 v90, v23
	v_pk_fma_f32 v[68:69], v[88:89], v[88:89], v[68:69]
	v_mov_b32_e32 v88, v13
	v_mov_b32_e32 v89, v9
	v_mov_b32_e32 v91, v19
	v_mov_b32_e32 v86, v12
	v_mov_b32_e32 v87, v8
	v_pk_mul_f32 v[88:89], v[88:89], v[88:89]
	v_pk_fma_f32 v[68:69], v[90:91], v[90:91], v[68:69]
	v_mov_b32_e32 v90, v14
	v_mov_b32_e32 v91, v10
	v_pk_fma_f32 v[86:87], v[86:87], v[86:87], v[88:89]
	v_mov_b32_e32 v92, v15
	v_mov_b32_e32 v93, v11
	v_pk_fma_f32 v[86:87], v[90:91], v[90:91], v[86:87]
	v_add_f32_e32 v31, v68, v69
	v_pk_fma_f32 v[86:87], v[92:93], v[92:93], v[86:87]
	v_lshlrev_b32_e32 v68, 2, v30
	v_add_f32_e32 v31, v31, v86
	v_add_f32_e32 v31, v31, v87
	ds_bpermute_b32 v33, v27, v31
	v_mov_b32_e32 v69, v165
	v_lshl_add_u64 v[86:87], v[82:83], 0, v[68:69]
	s_waitcnt lgkmcnt(0)
	v_add_f32_e32 v31, v31, v33
	ds_swizzle_b32 v33, v31 offset:swizzle(SWAP,16)
	s_waitcnt lgkmcnt(0)
	v_add_f32_e32 v31, v31, v33
	ds_swizzle_b32 v33, v31 offset:swizzle(SWAP,8)
	s_waitcnt lgkmcnt(0)
	v_add_f32_e32 v31, v31, v33
	ds_swizzle_b32 v33, v31 offset:swizzle(SWAP,4)
	s_waitcnt lgkmcnt(0)
	v_add_f32_e32 v31, v31, v33
	ds_swizzle_b32 v33, v31 offset:swizzle(SWAP,2)
	s_waitcnt lgkmcnt(0)
	v_add_f32_e32 v31, v31, v33
	ds_swizzle_b32 v33, v31 offset:swizzle(SWAP,1)
	s_waitcnt lgkmcnt(0)
	v_add_f32_e32 v31, v31, v33
	v_fmamk_f32 v31, v31, 0x3a800000, v189
	v_mul_f32_e32 v33, 0x4b800000, v31
	v_cmp_gt_f32_e32 vcc, s28, v31
	v_add_f32_e32 v35, 1.0, v79
	v_cndmask_b32_e32 v31, v31, v33, vcc
	v_rsq_f32_e32 v31, v31
	v_add_f32_e32 v41, 1.0, v80
	v_add_f32_e32 v51, 1.0, v81
	v_mul_f32_e32 v33, 0x45800000, v31
	v_cndmask_b32_e32 v31, v31, v33, vcc
	v_mul_f32_e32 v20, v20, v31
	v_mul_f32_e32 v21, v21, v31
	v_mul_f32_e32 v22, v22, v31
	v_mul_f32_e32 v23, v23, v31
	v_mul_f32_e32 v20, v70, v20
	v_mul_f32_e32 v21, v71, v21
	v_add_f32_e32 v33, 1.0, v78
	v_mul_f32_e32 v22, v72, v22
	v_mul_f32_e32 v23, v73, v23
	v_fma_f32 v20, v33, v20, v74
	v_fma_f32 v21, v35, v21, v75
	v_fma_f32 v22, v22, v41, v76
	v_fmac_f32_e32 v77, v23, v51
	v_cvt_pk_bf16_f32 v20, v20, v21
	v_cvt_pk_bf16_f32 v21, v22, v77
	global_store_dwordx2 v[38:39], v[20:21], off
	v_mov_b32_e32 v70, v202
	v_mov_b32_e32 v71, v203
	v_mov_b32_e32 v72, v204
	v_mov_b32_e32 v73, v205
	v_mov_b32_e32 v74, v240
	v_mov_b32_e32 v75, v241
	v_mov_b32_e32 v76, v242
	v_mov_b32_e32 v77, v243
	v_mov_b32_e32 v78, v218
	v_mov_b32_e32 v79, v219
	v_mov_b32_e32 v80, v220
	v_mov_b32_e32 v81, v221
	v_mul_f32_e32 v16, v16, v31
	v_mul_f32_e32 v17, v17, v31
	v_mul_f32_e32 v18, v18, v31
	v_mul_f32_e32 v19, v19, v31
	v_lshlrev_b32_e32 v20, 2, v32
	v_mov_b32_e32 v21, v165
	v_lshl_add_u64 v[22:23], v[82:83], 0, v[20:21]
	v_mul_f32_e32 v12, v12, v31
	v_mul_f32_e32 v13, v13, v31
	v_mul_f32_e32 v14, v14, v31
	v_mul_f32_e32 v15, v15, v31
	v_mul_f32_e32 v8, v8, v31
	v_mul_f32_e32 v9, v9, v31
	v_mul_f32_e32 v10, v10, v31
	v_mul_f32_e32 v11, v11, v31
	v_mul_f32_e32 v16, v16, v70
	v_add_f32_e32 v33, 1.0, v74
	v_mul_f32_e32 v17, v17, v71
	v_add_f32_e32 v35, 1.0, v75
	v_mul_f32_e32 v18, v18, v72
	v_add_f32_e32 v41, 1.0, v76
	v_mul_f32_e32 v19, v19, v73
	v_add_f32_e32 v51, 1.0, v77
	v_fma_f32 v16, v16, v33, v78
	v_fma_f32 v17, v17, v35, v79
	v_fma_f32 v18, v18, v41, v80
	v_fmac_f32_e32 v81, v19, v51
	v_cvt_pk_bf16_f32 v16, v16, v17
	v_cvt_pk_bf16_f32 v17, v18, v81
	global_store_dwordx2 v[38:39], v[16:17], off offset:512
	v_mov_b32_e32 v70, v206
	v_mov_b32_e32 v71, v207
	v_mov_b32_e32 v72, v208
	v_mov_b32_e32 v73, v209
	v_mov_b32_e32 v74, v244
	v_mov_b32_e32 v75, v245
	v_mov_b32_e32 v76, v246
	v_mov_b32_e32 v77, v247
	v_mov_b32_e32 v78, v222
	v_mov_b32_e32 v79, v223
	v_mov_b32_e32 v80, v224
	v_mov_b32_e32 v81, v225
	v_lshlrev_b32_e32 v16, 2, v34
	v_mov_b32_e32 v17, v165
	v_lshl_add_u64 v[18:19], v[82:83], 0, v[16:17]
	v_mul_f32_e32 v12, v12, v70
	v_add_f32_e32 v22, 1.0, v74
	v_mul_f32_e32 v13, v13, v71
	v_add_f32_e32 v23, 1.0, v75
	v_mul_f32_e32 v14, v14, v72
	v_add_f32_e32 v33, 1.0, v76
	v_mul_f32_e32 v15, v15, v73
	v_add_f32_e32 v35, 1.0, v77
	v_fma_f32 v12, v12, v22, v78
	v_fma_f32 v13, v13, v23, v79
	v_fma_f32 v14, v14, v33, v80
	v_fmac_f32_e32 v81, v15, v35
	v_cvt_pk_bf16_f32 v12, v12, v13
	v_cvt_pk_bf16_f32 v13, v14, v81
	global_store_dwordx2 v[38:39], v[12:13], off offset:1024
	v_mov_b32_e32 v12, v210
	v_mov_b32_e32 v13, v211
	v_mov_b32_e32 v14, v212
	v_mov_b32_e32 v15, v213
	s_nop 0
	v_mov_b32_e32 v70, v248
	v_mov_b32_e32 v71, v249
	v_mov_b32_e32 v72, v250
	v_mov_b32_e32 v73, v251
	v_mov_b32_e32 v74, v226
	v_mov_b32_e32 v75, v227
	v_mov_b32_e32 v76, v228
	v_mov_b32_e32 v77, v229
	v_mul_f32_e32 v8, v8, v12
	v_add_f32_e32 v12, 1.0, v70
	v_mul_f32_e32 v9, v9, v13
	v_add_f32_e32 v13, 1.0, v71
	v_mul_f32_e32 v10, v10, v14
	v_add_f32_e32 v14, 1.0, v72
	v_mul_f32_e32 v11, v11, v15
	v_add_f32_e32 v15, 1.0, v73
	v_fma_f32 v8, v8, v12, v74
	v_fma_f32 v9, v9, v13, v75
	v_fma_f32 v10, v10, v14, v76
	v_fmac_f32_e32 v77, v11, v15
	v_cvt_pk_bf16_f32 v8, v8, v9
	v_cvt_pk_bf16_f32 v9, v10, v77
	global_store_dwordx2 v[38:39], v[8:9], off offset:1536
	s_and_saveexec_b64 s[14:15], s[34:35]
	s_cbranch_execz .LBB0_148
	v_add_u32_e32 v8, 0xffffe000, v50
	v_lshrrev_b32_e32 v8, 12, v8
	v_add_u32_e32 v8, 1, v8
	v_cmp_lt_i32_e32 vcc, s48, v50
	v_mov_b64_e32 v[12:13], s[4:5]
	v_pk_mul_f32 v[60:61], v[60:61], v[60:61]
	v_cndmask_b32_e32 v8, 0, v8, vcc
	v_add_u32_e32 v14, s69, v8
	v_mad_u64_u32 v[18:19], s[6:7], v14, s50, v[12:13]
	v_lshl_add_u64 v[22:23], v[18:19], 0, s[58:59]
	v_lshl_add_u64 v[12:13], v[22:23], 0, v[164:165]
	v_lshl_add_u64 v[74:75], v[18:19], 0, v[164:165]
	v_pk_mul_f32 v[18:19], v[66:67], v[66:67]
	v_mov_b32_e32 v254, v12
	v_mov_b32_e32 v255, v13
	global_load_dwordx4 v[214:217], v[74:75], off
	global_load_dwordx4 v[218:221], v[74:75], off offset:1024
	global_load_dwordx4 v[222:225], v[74:75], off offset:2048
	global_load_dwordx4 v[226:229], v[74:75], off offset:3072
	global_load_dwordx4 v[230:233], v[254:255], off
	global_load_dwordx4 v[240:243], v[254:255], off offset:1024
	global_load_dwordx4 v[244:247], v[254:255], off offset:2048
	global_load_dwordx4 v[248:251], v[254:255], off offset:3072
	s_waitcnt vmcnt(0)
	v_mov_b32_e32 v8, v198
	v_mov_b32_e32 v9, v199
	v_mov_b32_e32 v10, v200
	v_mov_b32_e32 v11, v201
	v_mov_b32_e32 v12, v230
	v_mov_b32_e32 v13, v231
	v_mov_b32_e32 v14, v232
	v_mov_b32_e32 v15, v233
	v_mov_b32_e32 v70, v214
	v_mov_b32_e32 v71, v215
	v_mov_b32_e32 v72, v216
	v_mov_b32_e32 v73, v217
	v_pk_fma_f32 v[18:19], v[64:65], v[64:65], v[18:19]
	v_pk_fma_f32 v[56:57], v[56:57], v[56:57], v[60:61]
	v_pk_fma_f32 v[18:19], v[62:63], v[62:63], v[18:19]
	v_pk_fma_f32 v[54:55], v[54:55], v[54:55], v[56:57]
	v_pk_fma_f32 v[18:19], v[58:59], v[58:59], v[18:19]
	v_pk_fma_f32 v[52:53], v[52:53], v[52:53], v[54:55]
	v_add_f32_e32 v18, v18, v19
	v_add_f32_e32 v18, v53, v18
	v_add_f32_e32 v18, v52, v18
	ds_bpermute_b32 v19, v27, v18
	v_ashrrev_i32_e32 v51, 31, v50
	v_lshl_add_u64 v[16:17], v[22:23], 0, v[16:17]
	s_waitcnt lgkmcnt(0)
	v_add_f32_e32 v18, v18, v19
	ds_swizzle_b32 v19, v18 offset:swizzle(SWAP,16)
	s_waitcnt lgkmcnt(0)
	v_add_f32_e32 v18, v18, v19
	ds_swizzle_b32 v19, v18 offset:swizzle(SWAP,8)
	s_waitcnt lgkmcnt(0)
	v_add_f32_e32 v18, v18, v19
	ds_swizzle_b32 v19, v18 offset:swizzle(SWAP,4)
	s_waitcnt lgkmcnt(0)
	v_add_f32_e32 v18, v18, v19
	ds_swizzle_b32 v19, v18 offset:swizzle(SWAP,2)
	s_waitcnt lgkmcnt(0)
	v_add_f32_e32 v18, v18, v19
	ds_swizzle_b32 v19, v18 offset:swizzle(SWAP,1)
	s_waitcnt lgkmcnt(0)
	v_add_f32_e32 v18, v18, v19
	v_fmamk_f32 v18, v18, 0x3a800000, v189
	v_mul_f32_e32 v19, 0x4b800000, v18
	v_cmp_gt_f32_e32 vcc, s28, v18
	v_add_f32_e32 v12, 1.0, v12
	v_cndmask_b32_e32 v18, v18, v19, vcc
	v_rsq_f32_e32 v31, v18
	v_lshlrev_b64 v[18:19], 11, v[50:51]
	v_add_f32_e32 v13, 1.0, v13
	v_lshl_add_u64 v[54:55], v[36:37], 0, v[18:19]
	v_mul_f32_e32 v33, 0x45800000, v31
	v_cndmask_b32_e32 v31, v31, v33, vcc
	v_mul_f32_e32 v33, v49, v31
	v_mul_f32_e32 v35, v5, v31
	v_mul_f32_e32 v41, v47, v31
	v_mul_f32_e32 v50, v7, v31
	v_mul_f32_e32 v8, v8, v33
	v_mul_f32_e32 v9, v9, v35
	v_mul_f32_e32 v10, v10, v41
	v_mul_f32_e32 v11, v11, v50
	v_add_f32_e32 v14, 1.0, v14
	v_add_f32_e32 v15, 1.0, v15
	v_fma_f32 v8, v12, v8, v70
	v_fma_f32 v9, v13, v9, v71
	v_fma_f32 v10, v10, v14, v72
	v_fmac_f32_e32 v73, v11, v15
	v_cvt_pk_bf16_f32 v8, v8, v9
	v_cvt_pk_bf16_f32 v9, v10, v73
	global_store_dwordx2 v[54:55], v[8:9], off
	v_lshl_add_u64 v[18:19], v[22:23], 0, v[68:69]
	v_mov_b32_e32 v8, v202
	v_mov_b32_e32 v9, v203
	v_mov_b32_e32 v10, v204
	v_mov_b32_e32 v11, v205
	v_mov_b32_e32 v12, v240
	v_mov_b32_e32 v13, v241
	v_mov_b32_e32 v14, v242
	v_mov_b32_e32 v15, v243
	v_mov_b32_e32 v50, v218
	v_mov_b32_e32 v51, v219
	v_mov_b32_e32 v52, v220
	v_mov_b32_e32 v53, v221
	v_lshl_add_u64 v[18:19], v[22:23], 0, v[20:21]
	v_mul_f32_e32 v20, v48, v31
	v_mul_f32_e32 v21, v4, v31
	v_mul_f32_e32 v33, v46, v31
	v_mul_f32_e32 v35, v6, v31
	v_mul_f32_e32 v22, v45, v31
	v_mul_f32_e32 v23, v1, v31
	v_mul_f32_e32 v8, v20, v8
	v_add_f32_e32 v12, 1.0, v12
	v_mul_f32_e32 v9, v21, v9
	v_add_f32_e32 v13, 1.0, v13
	v_mul_f32_e32 v10, v33, v10
	v_add_f32_e32 v14, 1.0, v14
	v_mul_f32_e32 v11, v35, v11
	v_add_f32_e32 v15, 1.0, v15
	v_fma_f32 v8, v8, v12, v50
	v_fma_f32 v9, v9, v13, v51
	v_fma_f32 v10, v10, v14, v52
	v_fmac_f32_e32 v53, v11, v15
	v_cvt_pk_bf16_f32 v8, v8, v9
	v_cvt_pk_bf16_f32 v9, v10, v53
	global_store_dwordx2 v[54:55], v[8:9], off offset:512
	v_mov_b32_e32 v8, v206
	v_mov_b32_e32 v9, v207
	v_mov_b32_e32 v10, v208
	v_mov_b32_e32 v11, v209
	s_nop 0
	v_mov_b32_e32 v12, v244
	v_mov_b32_e32 v13, v245
	v_mov_b32_e32 v14, v246
	v_mov_b32_e32 v15, v247
	s_nop 0
	v_mov_b32_e32 v18, v222
	v_mov_b32_e32 v19, v223
	v_mov_b32_e32 v20, v224
	v_mov_b32_e32 v21, v225
	v_mul_f32_e32 v33, v43, v31
	v_mul_f32_e32 v35, v3, v31
	v_mul_f32_e32 v8, v22, v8
	v_add_f32_e32 v12, 1.0, v12
	v_mul_f32_e32 v9, v23, v9
	v_add_f32_e32 v13, 1.0, v13
	v_mul_f32_e32 v10, v33, v10
	v_add_f32_e32 v14, 1.0, v14
	v_mul_f32_e32 v11, v35, v11
	v_add_f32_e32 v15, 1.0, v15
	v_fma_f32 v8, v8, v12, v18
	v_fma_f32 v9, v9, v13, v19
	v_fma_f32 v10, v10, v14, v20
	v_fmac_f32_e32 v21, v11, v15
	v_cvt_pk_bf16_f32 v8, v8, v9
	v_cvt_pk_bf16_f32 v9, v10, v21
	global_store_dwordx2 v[54:55], v[8:9], off offset:1024
	v_mov_b32_e32 v8, v210
	v_mov_b32_e32 v9, v211
	v_mov_b32_e32 v10, v212
	v_mov_b32_e32 v11, v213
	s_nop 0
	v_mov_b32_e32 v12, v248
	v_mov_b32_e32 v13, v249
	v_mov_b32_e32 v14, v250
	v_mov_b32_e32 v15, v251
	s_nop 0
	v_mov_b32_e32 v16, v226
	v_mov_b32_e32 v17, v227
	v_mov_b32_e32 v18, v228
	v_mov_b32_e32 v19, v229
	v_mul_f32_e32 v20, v44, v31
	v_mul_f32_e32 v21, v0, v31
	v_mul_f32_e32 v22, v42, v31
	v_mul_f32_e32 v23, v2, v31
	v_mul_f32_e32 v8, v20, v8
	v_add_f32_e32 v12, 1.0, v12
	v_mul_f32_e32 v9, v21, v9
	v_add_f32_e32 v13, 1.0, v13
	v_mul_f32_e32 v10, v22, v10
	v_add_f32_e32 v14, 1.0, v14
	v_mul_f32_e32 v11, v23, v11
	v_add_f32_e32 v15, 1.0, v15
	v_fma_f32 v8, v8, v12, v16
	v_fma_f32 v9, v9, v13, v17
	v_fma_f32 v10, v10, v14, v18
	v_fmac_f32_e32 v19, v11, v15
	v_cvt_pk_bf16_f32 v8, v8, v9
	v_cvt_pk_bf16_f32 v9, v10, v19
	global_store_dwordx2 v[54:55], v[8:9], off offset:1536
	s_branch .LBB0_148

.LBB0_711:
	s_waitcnt lgkmcnt(10)
	v_mfma_f32_32x32x16_bf16 v[48:63], v[198:201], v[240:243], v[48:63]
	v_add_u32_e32 v177, s100, v153
	ds_read_b128 v[198:201], v177 offset:36864
	v_sub_f32_e32 v186, v64, v160
	v_exp_f32_e32 v186, v186
	v_sub_f32_e32 v187, v65, v160
	v_exp_f32_e32 v187, v187
	v_add_f32_e32 v234, v186, v234
	v_add_f32_e32 v234, v187, v234
	v_cvt_pk_bf16_f32 v248, v186, v187
	s_waitcnt lgkmcnt(10)
	v_mfma_f32_32x32x16_bf16 v[32:47], v[202:205], v[240:243], v[32:47]
	v_add_u32_e32 v177, s100, v152
	ds_read_b128 v[202:205], v177 offset:24576
	v_sub_f32_e32 v170, v66, v160
	v_exp_f32_e32 v170, v170
	v_sub_f32_e32 v171, v67, v160
	v_exp_f32_e32 v171, v171
	v_add_f32_e32 v234, v170, v234
	v_add_f32_e32 v234, v171, v234
	v_cvt_pk_bf16_f32 v249, v170, v171
	s_waitcnt lgkmcnt(10)
	v_mfma_f32_32x32x16_bf16 v[16:31], v[206:209], v[240:243], v[16:31]
	v_add_u32_e32 v177, s100, v152
	ds_read_b128 v[206:209], v177 offset:28672
	v_sub_f32_e32 v172, v68, v160
	v_exp_f32_e32 v172, v172
	v_sub_f32_e32 v173, v69, v160
	v_exp_f32_e32 v173, v173
	v_add_f32_e32 v234, v172, v234
	v_add_f32_e32 v234, v173, v234
	v_cvt_pk_bf16_f32 v250, v172, v173
	s_waitcnt lgkmcnt(10)
	v_mfma_f32_32x32x16_bf16 v[0:15], v[210:213], v[240:243], v[0:15]
	v_add_u32_e32 v177, s100, v152
	ds_read_b128 v[210:213], v177 offset:32768
	v_sub_f32_e32 v186, v70, v160
	v_exp_f32_e32 v186, v186
	v_sub_f32_e32 v187, v71, v160
	v_exp_f32_e32 v187, v187
	v_add_f32_e32 v234, v186, v234
	v_add_f32_e32 v234, v187, v234
	v_cvt_pk_bf16_f32 v251, v186, v187
	s_waitcnt lgkmcnt(10)
	v_mfma_f32_32x32x16_bf16 v[48:63], v[214:217], v[244:247], v[48:63]
	v_add_u32_e32 v177, s100, v152
	ds_read_b128 v[214:217], v177 offset:36864
	v_sub_f32_e32 v170, v72, v160
	v_exp_f32_e32 v170, v170
	v_sub_f32_e32 v171, v73, v160
	v_exp_f32_e32 v171, v171
	v_add_f32_e32 v234, v170, v234
	v_add_f32_e32 v234, v171, v234
	v_cvt_pk_bf16_f32 v252, v170, v171
	s_waitcnt lgkmcnt(10)
	v_mfma_f32_32x32x16_bf16 v[32:47], v[218:221], v[244:247], v[32:47]
	v_sub_f32_e32 v172, v74, v160
	v_exp_f32_e32 v172, v172
	v_sub_f32_e32 v173, v75, v160
	v_exp_f32_e32 v173, v173
	v_add_f32_e32 v234, v172, v234
	v_add_f32_e32 v234, v173, v234
	v_cvt_pk_bf16_f32 v253, v172, v173
	s_waitcnt lgkmcnt(9)
	v_mfma_f32_32x32x16_bf16 v[16:31], v[222:225], v[244:247], v[16:31]
	v_sub_f32_e32 v186, v76, v160
	v_exp_f32_e32 v186, v186
	v_sub_f32_e32 v187, v77, v160
	v_exp_f32_e32 v187, v187
	v_add_f32_e32 v234, v186, v234
	v_add_f32_e32 v234, v187, v234
	v_cvt_pk_bf16_f32 v254, v186, v187
	s_waitcnt lgkmcnt(8)
	v_mfma_f32_32x32x16_bf16 v[0:15], v[226:229], v[244:247], v[0:15]
	v_sub_f32_e32 v170, v78, v160
	v_exp_f32_e32 v170, v170
	v_sub_f32_e32 v171, v79, v160
	v_exp_f32_e32 v171, v171
	v_add_f32_e32 v234, v170, v234
	v_add_f32_e32 v234, v171, v234
	v_cvt_pk_bf16_f32 v255, v170, v171
	s_waitcnt lgkmcnt(7)
	v_mfma_f32_32x32x16_bf16 v[48:63], v[230:233], v[248:251], v[48:63]
	s_waitcnt lgkmcnt(6)
	v_mfma_f32_32x32x16_bf16 v[32:47], v[178:181], v[248:251], v[32:47]
	s_waitcnt lgkmcnt(5)
	v_mfma_f32_32x32x16_bf16 v[16:31], v[182:185], v[248:251], v[16:31]
	s_waitcnt lgkmcnt(4)
	v_mfma_f32_32x32x16_bf16 v[0:15], v[198:201], v[248:251], v[0:15]
	s_waitcnt lgkmcnt(3)
	v_mfma_f32_32x32x16_bf16 v[48:63], v[202:205], v[252:255], v[48:63]
	s_waitcnt lgkmcnt(2)
	v_mfma_f32_32x32x16_bf16 v[32:47], v[206:209], v[252:255], v[32:47]
	s_waitcnt lgkmcnt(1)
	v_mfma_f32_32x32x16_bf16 v[16:31], v[210:213], v[252:255], v[16:31]
	s_waitcnt lgkmcnt(0)
	v_mfma_f32_32x32x16_bf16 v[0:15], v[214:217], v[252:255], v[0:15]
	v_add_f32_e32 v147, v147, v234
	s_nop 0
	s_waitcnt vmcnt(0)
	s_add_i32 s14, s14, 1
	s_add_i32 s13, s13, 64
	v_lshl_add_u64 v[148:149], v[148:149], 0, s[18:19]
	s_cmp_eq_u32 s17, s14
	v_lshl_add_u64 v[150:151], v[150:151], 0, s[18:19]
	s_waitcnt vmcnt(0)
	s_barrier
	s_cbranch_scc1 .LBB0_722

.LBB0_720:
	s_ashr_i32 s11, s10, 31
	s_lshl_b64 s[6:7], s[10:11], 3
	s_add_u32 s6, s6, s4
	s_addc_u32 s7, s7, s5
	s_mulk_i32 s7, 0x180
	s_mul_hi_u32 s10, s6, 0x180
	s_add_i32 s10, s10, s7
	s_mulk_i32 s6, 0x180
	s_add_u32 s6, s15, s6
	s_addc_u32 s7, s16, s10
	s_bitcmp1_b32 s14, 0
	s_cselect_b32 s10, 0xa000, 0
	v_add_u32_e32 v66, s10, v162
	v_add_u32_e32 v67, 0x2000, v66
	v_readfirstlane_b32 s11, v66
	v_lshl_add_u64 v[64:65], s[6:7], 0, v[164:165]
	s_mov_b32 m0, s11
	v_readfirstlane_b32 s11, v67
	global_load_lds_dwordx4 v[64:65], off
	v_lshl_add_u64 v[64:65], s[6:7], 0, v[154:155]
	s_mov_b32 m0, s11
	v_add_u32_e32 v66, 0x4000, v66
	global_load_lds_dwordx4 v[64:65], off
	v_lshl_add_u64 v[64:65], s[6:7], 0, v[156:157]
	v_readfirstlane_b32 s6, v66
	s_mov_b32 m0, s6
	s_cselect_b32 s7, 0, 0xa000
	s_add_i32 s6, s10, 0
	global_load_lds_dwordx4 v[64:65], off
	v_add_u32_e32 v64, s6, v161
	v_add_u32_e32 v65, 0x6000, v64
	v_add_u32_e32 v64, 0x8000, v64
	v_readfirstlane_b32 s10, v65
	s_mov_b32 m0, s10
	v_readfirstlane_b32 s10, v64
	global_load_lds_dwordx4 v[150:151], off
	s_mov_b32 m0, s10
	s_add_i32 s7, s7, 0
	global_load_lds_dwordx4 v[148:149], off
	s_nop 0
	s_waitcnt lgkmcnt(10)
	v_mfma_f32_32x32x16_bf16 v[80:95], v[178:181], v[116:119], 0
	ds_read_b128 v[178:181], v176 offset:256
	s_waitcnt lgkmcnt(10)
	v_mfma_f32_32x32x16_bf16 v[80:95], v[182:185], v[124:127], v[80:95]
	ds_read_b128 v[182:185], v169 offset:12288
	s_waitcnt lgkmcnt(10)
	v_mfma_f32_32x32x16_bf16 v[80:95], v[198:201], v[132:135], v[80:95]
	ds_read_b128 v[198:201], v174 offset:12288
	s_waitcnt lgkmcnt(10)
	v_mfma_f32_32x32x16_bf16 v[80:95], v[202:205], v[136:139], v[80:95]
	ds_read_b128 v[202:205], v175 offset:12288
	s_waitcnt lgkmcnt(10)
	v_mfma_f32_32x32x16_bf16 v[80:95], v[206:209], v[104:107], v[80:95]
	ds_read_b128 v[206:209], v176 offset:12288
	s_waitcnt lgkmcnt(10)
	v_mfma_f32_32x32x16_bf16 v[80:95], v[210:213], v[112:115], v[80:95]
	ds_read_b128 v[210:213], v169 offset:12416
	s_waitcnt lgkmcnt(10)
	v_mfma_f32_32x32x16_bf16 v[80:95], v[214:217], v[120:123], v[80:95]
	ds_read_b128 v[214:217], v174 offset:12416
	s_waitcnt lgkmcnt(10)
	v_mfma_f32_32x32x16_bf16 v[80:95], v[218:221], v[128:131], v[80:95]
	ds_read_b128 v[218:221], v175 offset:12416
	s_waitcnt lgkmcnt(10)
	v_mfma_f32_32x32x16_bf16 v[80:95], v[222:225], v[100:103], v[80:95]
	ds_read_b128 v[222:225], v176 offset:12416
	s_waitcnt lgkmcnt(10)
	v_mfma_f32_32x32x16_bf16 v[80:95], v[226:229], v[96:99], v[80:95]
	ds_read_b128 v[226:229], v169 offset:12544
	s_waitcnt lgkmcnt(10)
	v_mfma_f32_32x32x16_bf16 v[80:95], v[230:233], v[140:143], v[80:95]
	ds_read_b128 v[230:233], v174 offset:12544
	s_waitcnt lgkmcnt(10)
	v_mfma_f32_32x32x16_bf16 v[80:95], v[178:181], v[108:111], v[80:95]
	ds_read_b128 v[178:181], v175 offset:12544
	s_waitcnt lgkmcnt(10)
	v_mfma_f32_32x32x16_bf16 v[64:79], v[182:185], v[116:119], 0
	ds_read_b128 v[182:185], v176 offset:12544
	s_waitcnt lgkmcnt(10)
	v_mfma_f32_32x32x16_bf16 v[64:79], v[198:201], v[124:127], v[64:79]
	v_add_u32_e32 v177, s100, v159
	ds_read_b128 v[198:201], v177 offset:24576
	s_waitcnt lgkmcnt(10)
	v_mfma_f32_32x32x16_bf16 v[64:79], v[202:205], v[132:135], v[64:79]
	ds_read_b128 v[202:205], v177 offset:28672
	s_waitcnt lgkmcnt(10)
	v_mfma_f32_32x32x16_bf16 v[64:79], v[206:209], v[136:139], v[64:79]
	ds_read_b128 v[206:209], v177 offset:32768
	v_sub_f32_e32 v170, v80, v160
	v_exp_f32_e32 v170, v170
	v_sub_f32_e32 v171, v81, v160
	v_exp_f32_e32 v171, v171
	v_add_f32_e32 v234, 0, v170
	v_add_f32_e32 v234, v171, v234
	s_waitcnt lgkmcnt(10)
	v_mfma_f32_32x32x16_bf16 v[64:79], v[210:213], v[104:107], v[64:79]
	ds_read_b128 v[210:213], v177 offset:36864
	v_cvt_pk_bf16_f32 v240, v170, v171
	v_sub_f32_e32 v172, v82, v160
	v_exp_f32_e32 v172, v172
	v_sub_f32_e32 v173, v83, v160
	v_exp_f32_e32 v173, v173
	v_add_f32_e32 v234, v172, v234
	s_waitcnt lgkmcnt(10)
	v_mfma_f32_32x32x16_bf16 v[64:79], v[214:217], v[112:115], v[64:79]
	v_add_u32_e32 v177, s100, v158
	ds_read_b128 v[214:217], v177 offset:24576
	v_add_f32_e32 v234, v173, v234
	v_cvt_pk_bf16_f32 v241, v172, v173
	v_sub_f32_e32 v186, v84, v160
	v_exp_f32_e32 v186, v186
	v_sub_f32_e32 v187, v85, v160
	v_exp_f32_e32 v187, v187
	s_waitcnt lgkmcnt(10)
	v_mfma_f32_32x32x16_bf16 v[64:79], v[218:221], v[120:123], v[64:79]
	ds_read_b128 v[218:221], v177 offset:28672
	v_add_f32_e32 v234, v186, v234
	v_add_f32_e32 v234, v187, v234
	v_cvt_pk_bf16_f32 v242, v186, v187
	v_sub_f32_e32 v170, v86, v160
	v_exp_f32_e32 v170, v170
	v_sub_f32_e32 v171, v87, v160
	s_waitcnt lgkmcnt(10)
	v_mfma_f32_32x32x16_bf16 v[64:79], v[222:225], v[128:131], v[64:79]
	ds_read_b128 v[222:225], v177 offset:32768
	v_exp_f32_e32 v171, v171
	v_add_f32_e32 v234, v170, v234
	v_add_f32_e32 v234, v171, v234
	v_cvt_pk_bf16_f32 v243, v170, v171
	v_sub_f32_e32 v172, v88, v160
	v_exp_f32_e32 v172, v172
	s_waitcnt lgkmcnt(10)
	v_mfma_f32_32x32x16_bf16 v[64:79], v[226:229], v[100:103], v[64:79]
	ds_read_b128 v[226:229], v177 offset:36864
	v_sub_f32_e32 v173, v89, v160
	v_exp_f32_e32 v173, v173
	v_add_f32_e32 v234, v172, v234
	v_add_f32_e32 v234, v173, v234
	v_cvt_pk_bf16_f32 v244, v172, v173
	v_sub_f32_e32 v186, v90, v160
	s_waitcnt lgkmcnt(10)
	v_mfma_f32_32x32x16_bf16 v[64:79], v[230:233], v[96:99], v[64:79]
	v_add_u32_e32 v177, s100, v153
	ds_read_b128 v[230:233], v177 offset:24576
	v_exp_f32_e32 v186, v186
	v_sub_f32_e32 v187, v91, v160
	v_exp_f32_e32 v187, v187
	v_add_f32_e32 v234, v186, v234
	v_add_f32_e32 v234, v187, v234
	v_cvt_pk_bf16_f32 v245, v186, v187
	s_waitcnt lgkmcnt(10)
	v_mfma_f32_32x32x16_bf16 v[64:79], v[178:181], v[140:143], v[64:79]
	ds_read_b128 v[178:181], v177 offset:28672
	v_sub_f32_e32 v170, v92, v160
	v_exp_f32_e32 v170, v170
	v_sub_f32_e32 v171, v93, v160
	v_exp_f32_e32 v171, v171
	v_add_f32_e32 v234, v170, v234
	v_add_f32_e32 v234, v171, v234
	s_waitcnt lgkmcnt(10)
	v_mfma_f32_32x32x16_bf16 v[64:79], v[182:185], v[108:111], v[64:79]
	ds_read_b128 v[182:185], v177 offset:32768
	v_cvt_pk_bf16_f32 v246, v170, v171
	v_sub_f32_e32 v172, v94, v160
	v_exp_f32_e32 v172, v172
	v_sub_f32_e32 v173, v95, v160
	v_exp_f32_e32 v173, v173
	v_add_f32_e32 v234, v172, v234
	v_add_f32_e32 v234, v173, v234
	v_cvt_pk_bf16_f32 v247, v172, v173
	v_max_f32_e32 v235, v80, v81
	v_max3_f32 v235, v235, v82, v83
	v_max3_f32 v235, v235, v84, v85
	v_max3_f32 v235, v235, v86, v87
	v_max3_f32 v235, v235, v88, v89
	v_max3_f32 v235, v235, v90, v91
	v_max3_f32 v235, v235, v92, v93
	v_max3_f32 v235, v235, v94, v95
	v_max3_f32 v169, v235, v64, v65
	v_max3_f32 v169, v169, v66, v67
	v_max3_f32 v169, v169, v68, v69
	v_max3_f32 v169, v169, v70, v71
	v_max3_f32 v169, v169, v72, v73
	v_max3_f32 v169, v169, v74, v75
	v_max3_f32 v169, v169, v76, v77
	v_max3_f32 v169, v169, v78, v79
	v_mov_b32_e32 v170, v169
	s_nop 1
	v_permlane32_swap_b32_e32 v169, v170
	v_max_f32_e32 v170, v170, v170
	v_max_f32_e32 v169, v169, v169
	v_max_f32_e32 v169, v169, v170
	v_sub_f32_e32 v170, v169, v160
	v_cmp_ge_f32_e32 vcc, s29, v170
	s_cmp_eq_u64 vcc, exec
	s_cbranch_scc1 .LBB0_711
	v_max_f32_e32 v169, v169, v169
	v_max_f32_e32 v170, v160, v160
	v_max_f32_e32 v169, v170, v169
	v_sub_f32_e32 v160, v160, v169
	v_exp_f32_e32 v160, v160
	s_nop 0
	v_pk_mul_f32 v[62:63], v[62:63], v[160:161] op_sel_hi:[1,0]
	v_pk_mul_f32 v[60:61], v[60:61], v[160:161] op_sel_hi:[1,0]
	v_pk_mul_f32 v[58:59], v[58:59], v[160:161] op_sel_hi:[1,0]
	v_pk_mul_f32 v[56:57], v[56:57], v[160:161] op_sel_hi:[1,0]
	v_pk_mul_f32 v[54:55], v[54:55], v[160:161] op_sel_hi:[1,0]
	v_pk_mul_f32 v[52:53], v[52:53], v[160:161] op_sel_hi:[1,0]
	v_pk_mul_f32 v[50:51], v[50:51], v[160:161] op_sel_hi:[1,0]
	v_pk_mul_f32 v[48:49], v[48:49], v[160:161] op_sel_hi:[1,0]
	v_pk_mul_f32 v[46:47], v[46:47], v[160:161] op_sel_hi:[1,0]
	v_pk_mul_f32 v[44:45], v[44:45], v[160:161] op_sel_hi:[1,0]
	v_pk_mul_f32 v[42:43], v[42:43], v[160:161] op_sel_hi:[1,0]
	v_pk_mul_f32 v[40:41], v[40:41], v[160:161] op_sel_hi:[1,0]
	v_pk_mul_f32 v[38:39], v[38:39], v[160:161] op_sel_hi:[1,0]
	v_pk_mul_f32 v[36:37], v[36:37], v[160:161] op_sel_hi:[1,0]
	v_pk_mul_f32 v[34:35], v[34:35], v[160:161] op_sel_hi:[1,0]
	v_pk_mul_f32 v[32:33], v[32:33], v[160:161] op_sel_hi:[1,0]
	v_pk_mul_f32 v[30:31], v[30:31], v[160:161] op_sel_hi:[1,0]
	v_pk_mul_f32 v[28:29], v[28:29], v[160:161] op_sel_hi:[1,0]
	v_pk_mul_f32 v[26:27], v[26:27], v[160:161] op_sel_hi:[1,0]
	v_pk_mul_f32 v[24:25], v[24:25], v[160:161] op_sel_hi:[1,0]
	v_pk_mul_f32 v[22:23], v[22:23], v[160:161] op_sel_hi:[1,0]
	v_pk_mul_f32 v[20:21], v[20:21], v[160:161] op_sel_hi:[1,0]
	v_pk_mul_f32 v[18:19], v[18:19], v[160:161] op_sel_hi:[1,0]
	v_pk_mul_f32 v[16:17], v[16:17], v[160:161] op_sel_hi:[1,0]
	v_pk_mul_f32 v[14:15], v[14:15], v[160:161] op_sel_hi:[1,0]
	v_pk_mul_f32 v[12:13], v[12:13], v[160:161] op_sel_hi:[1,0]
	v_pk_mul_f32 v[10:11], v[10:11], v[160:161] op_sel_hi:[1,0]
	v_pk_mul_f32 v[8:9], v[8:9], v[160:161] op_sel_hi:[1,0]
	v_pk_mul_f32 v[6:7], v[6:7], v[160:161] op_sel_hi:[1,0]
	v_pk_mul_f32 v[4:5], v[4:5], v[160:161] op_sel_hi:[1,0]
	v_pk_mul_f32 v[2:3], v[2:3], v[160:161] op_sel_hi:[1,0]
	v_pk_mul_f32 v[0:1], v[0:1], v[160:161] op_sel_hi:[1,0]
	v_mul_f32_e32 v147, v147, v160
	v_mov_b32_e32 v160, v169
	v_sub_f32_e32 v170, v80, v160
	v_exp_f32_e32 v170, v170
	v_sub_f32_e32 v171, v81, v160
	v_exp_f32_e32 v171, v171
	v_add_f32_e32 v234, 0, v170
	v_add_f32_e32 v234, v171, v234
	v_cvt_pk_bf16_f32 v240, v170, v171
	v_sub_f32_e32 v172, v82, v160
	v_exp_f32_e32 v172, v172
	v_sub_f32_e32 v173, v83, v160
	v_exp_f32_e32 v173, v173
	v_add_f32_e32 v234, v172, v234
	v_add_f32_e32 v234, v173, v234
	v_cvt_pk_bf16_f32 v241, v172, v173
	v_sub_f32_e32 v186, v84, v160
	v_exp_f32_e32 v186, v186
	v_sub_f32_e32 v187, v85, v160
	v_exp_f32_e32 v187, v187
	v_add_f32_e32 v234, v186, v234
	v_add_f32_e32 v234, v187, v234
	v_cvt_pk_bf16_f32 v242, v186, v187
	v_sub_f32_e32 v170, v86, v160
	v_exp_f32_e32 v170, v170
	v_sub_f32_e32 v171, v87, v160
	v_exp_f32_e32 v171, v171
	v_add_f32_e32 v234, v170, v234
	v_add_f32_e32 v234, v171, v234
	v_cvt_pk_bf16_f32 v243, v170, v171
	v_sub_f32_e32 v172, v88, v160
	v_exp_f32_e32 v172, v172
	v_sub_f32_e32 v173, v89, v160
	v_exp_f32_e32 v173, v173
	v_add_f32_e32 v234, v172, v234
	v_add_f32_e32 v234, v173, v234
	v_cvt_pk_bf16_f32 v244, v172, v173
	v_sub_f32_e32 v186, v90, v160
	v_exp_f32_e32 v186, v186
	v_sub_f32_e32 v187, v91, v160
	v_exp_f32_e32 v187, v187
	v_add_f32_e32 v234, v186, v234
	v_add_f32_e32 v234, v187, v234
	v_cvt_pk_bf16_f32 v245, v186, v187
	v_sub_f32_e32 v170, v92, v160
	v_exp_f32_e32 v170, v170
	v_sub_f32_e32 v171, v93, v160
	v_exp_f32_e32 v171, v171
	v_add_f32_e32 v234, v170, v234
	v_add_f32_e32 v234, v171, v234
	v_cvt_pk_bf16_f32 v246, v170, v171
	v_sub_f32_e32 v172, v94, v160
	v_exp_f32_e32 v172, v172
	v_sub_f32_e32 v173, v95, v160
	v_exp_f32_e32 v173, v173
	v_add_f32_e32 v234, v172, v234
	v_add_f32_e32 v234, v173, v234
	v_cvt_pk_bf16_f32 v247, v172, v173
	v_max_f32_e32 v235, v80, v81
	v_max3_f32 v235, v235, v82, v83
	v_max3_f32 v235, v235, v84, v85
	v_max3_f32 v235, v235, v86, v87
	v_max3_f32 v235, v235, v88, v89
	v_max3_f32 v235, v235, v90, v91
	v_max3_f32 v235, v235, v92, v93
	v_max3_f32 v235, v235, v94, v95
	s_branch .LBB0_711

.LBB0_802:
	s_bitcmp1_b32 s13, 0
	s_cselect_b32 s13, 0xc000, 0
	s_add_i32 s13, s13, 0
	s_add_i32 s15, s7, s13
	v_add_u32_e32 v96, s15, v75
	s_add_i32 s13, s6, s13
	v_add_u32_e32 v100, s13, v75
	ds_read_b128 v[76:79], v96
	ds_read_b128 v[84:87], v96 offset:1024
	ds_read_b128 v[92:95], v96 offset:2048
	ds_read_b128 v[96:99], v96 offset:3072
	ds_read_b128 v[80:83], v100 offset:16384
	ds_read_b128 v[88:91], v100 offset:17408
	ds_read_b128 v[198:201], v100 offset:18432
	ds_read_b128 v[202:205], v100 offset:19456
	ds_read_b128 v[206:209], v100 offset:20480
	ds_read_b128 v[210:213], v100 offset:21504
	s_waitcnt lgkmcnt(4)
	v_mfma_f32_16x16x32_bf16 v[64:67], v[92:95], v[80:83], v[64:67]
	s_add_u32 s10, s10, 0x80
	s_addc_u32 s11, s11, 0
	v_lshl_add_u64 v[70:71], v[70:71], 0, s[20:21]
	v_mfma_f32_16x16x32_bf16 v[48:51], v[76:79], v[80:83], v[48:51]
	v_lshl_add_u64 v[72:73], v[72:73], 0, s[20:21]
	s_cmpk_lg_i32 s10, 0x800
	s_mov_b32 s13, s14
	v_mfma_f32_16x16x32_bf16 v[48:51], v[84:87], v[88:91], v[48:51]
	v_mfma_f32_16x16x32_bf16 v[64:67], v[96:99], v[88:91], v[64:67]
	ds_read_b128 v[214:217], v100 offset:22528
	ds_read_b128 v[218:221], v100 offset:23552
	s_waitcnt lgkmcnt(4)
	v_mfma_f32_16x16x32_bf16 v[60:63], v[76:79], v[198:201], v[60:63]
	v_mfma_f32_16x16x32_bf16 v[56:59], v[92:95], v[198:201], v[56:59]
	v_mfma_f32_16x16x32_bf16 v[60:63], v[84:87], v[202:205], v[60:63]
	v_mfma_f32_16x16x32_bf16 v[56:59], v[96:99], v[202:205], v[56:59]
	ds_read_b128 v[80:83], v100 offset:32768
	ds_read_b128 v[88:91], v100 offset:33792
	s_waitcnt lgkmcnt(4)
	v_mfma_f32_16x16x32_bf16 v[44:47], v[76:79], v[206:209], v[44:47]
	v_mfma_f32_16x16x32_bf16 v[40:43], v[92:95], v[206:209], v[40:43]
	v_mfma_f32_16x16x32_bf16 v[44:47], v[84:87], v[210:213], v[44:47]
	v_mfma_f32_16x16x32_bf16 v[40:43], v[96:99], v[210:213], v[40:43]
	ds_read_b128 v[198:201], v100 offset:34816
	ds_read_b128 v[202:205], v100 offset:35840
	s_waitcnt lgkmcnt(4)
	v_mfma_f32_16x16x32_bf16 v[36:39], v[76:79], v[214:217], v[36:39]
	v_mfma_f32_16x16x32_bf16 v[32:35], v[92:95], v[214:217], v[32:35]
	v_mfma_f32_16x16x32_bf16 v[36:39], v[84:87], v[218:221], v[36:39]
	v_mfma_f32_16x16x32_bf16 v[32:35], v[96:99], v[218:221], v[32:35]
	ds_read_b128 v[206:209], v100 offset:36864
	ds_read_b128 v[210:213], v100 offset:37888
	s_waitcnt lgkmcnt(4)
	v_mfma_f32_16x16x32_bf16 v[28:31], v[76:79], v[80:83], v[28:31]
	v_mfma_f32_16x16x32_bf16 v[24:27], v[92:95], v[80:83], v[24:27]
	v_mfma_f32_16x16x32_bf16 v[28:31], v[84:87], v[88:91], v[28:31]
	v_mfma_f32_16x16x32_bf16 v[24:27], v[96:99], v[88:91], v[24:27]
	ds_read_b128 v[214:217], v100 offset:38912
	ds_read_b128 v[218:221], v100 offset:39936
	s_waitcnt lgkmcnt(4)
	v_mfma_f32_16x16x32_bf16 v[20:23], v[76:79], v[198:201], v[20:23]
	v_mfma_f32_16x16x32_bf16 v[8:11], v[92:95], v[198:201], v[8:11]
	v_mfma_f32_16x16x32_bf16 v[20:23], v[84:87], v[202:205], v[20:23]
	v_mfma_f32_16x16x32_bf16 v[8:11], v[96:99], v[202:205], v[8:11]
	s_waitcnt lgkmcnt(2)
	v_mfma_f32_16x16x32_bf16 v[16:19], v[76:79], v[206:209], v[16:19]
	v_mfma_f32_16x16x32_bf16 v[12:15], v[92:95], v[206:209], v[12:15]
	v_mfma_f32_16x16x32_bf16 v[16:19], v[84:87], v[210:213], v[16:19]
	v_mfma_f32_16x16x32_bf16 v[12:15], v[96:99], v[210:213], v[12:15]
	s_waitcnt vmcnt(0)
	s_waitcnt vmcnt(0) lgkmcnt(0)
	v_mfma_f32_16x16x32_bf16 v[4:7], v[76:79], v[214:217], v[4:7]
	s_barrier
	v_mfma_f32_16x16x32_bf16 v[0:3], v[92:95], v[214:217], v[0:3]
	v_mfma_f32_16x16x32_bf16 v[4:7], v[84:87], v[218:221], v[4:7]
	v_mfma_f32_16x16x32_bf16 v[0:3], v[96:99], v[218:221], v[0:3]
	s_cbranch_scc0 .LBB0_805

.LBB0_900:
	s_bitcmp1_b32 s8, 0
	s_cselect_b32 s8, 0xc000, 0
	s_add_i32 s8, s8, 0
	s_add_i32 s10, s6, s8
	v_add_u32_e32 v75, s10, v74
	s_add_i32 s8, s2, s8
	v_add_u32_e32 v100, s8, v74
	ds_read_b128 v[76:79], v75
	ds_read_b128 v[84:87], v75 offset:1024
	ds_read_b128 v[92:95], v75 offset:2048
	ds_read_b128 v[96:99], v75 offset:3072
	ds_read_b128 v[80:83], v100 offset:16384
	ds_read_b128 v[88:91], v100 offset:17408
	ds_read_b128 v[198:201], v100 offset:18432
	ds_read_b128 v[202:205], v100 offset:19456
	ds_read_b128 v[206:209], v100 offset:20480
	ds_read_b128 v[210:213], v100 offset:21504
	s_waitcnt lgkmcnt(4)
	v_mfma_f32_16x16x32_bf16 v[56:59], v[92:95], v[80:83], v[56:59]
	s_add_u32 s4, s4, 0x80
	s_addc_u32 s5, s5, 0
	v_lshl_add_u64 v[68:69], v[68:69], 0, s[14:15]
	v_mfma_f32_16x16x32_bf16 v[60:63], v[76:79], v[80:83], v[60:63]
	v_lshl_add_u64 v[70:71], v[70:71], 0, s[14:15]
	s_cmpk_lg_i32 s4, 0x800
	s_mov_b32 s8, s9
	v_mfma_f32_16x16x32_bf16 v[60:63], v[84:87], v[88:91], v[60:63]
	v_mfma_f32_16x16x32_bf16 v[56:59], v[96:99], v[88:91], v[56:59]
	ds_read_b128 v[214:217], v100 offset:22528
	ds_read_b128 v[218:221], v100 offset:23552
	s_waitcnt lgkmcnt(4)
	v_mfma_f32_16x16x32_bf16 v[52:55], v[76:79], v[198:201], v[52:55]
	v_mfma_f32_16x16x32_bf16 v[48:51], v[92:95], v[198:201], v[48:51]
	v_mfma_f32_16x16x32_bf16 v[52:55], v[84:87], v[202:205], v[52:55]
	v_mfma_f32_16x16x32_bf16 v[48:51], v[96:99], v[202:205], v[48:51]
	ds_read_b128 v[80:83], v100 offset:32768
	ds_read_b128 v[88:91], v100 offset:33792
	s_waitcnt lgkmcnt(4)
	v_mfma_f32_16x16x32_bf16 v[44:47], v[76:79], v[206:209], v[44:47]
	v_mfma_f32_16x16x32_bf16 v[40:43], v[92:95], v[206:209], v[40:43]
	v_mfma_f32_16x16x32_bf16 v[44:47], v[84:87], v[210:213], v[44:47]
	v_mfma_f32_16x16x32_bf16 v[40:43], v[96:99], v[210:213], v[40:43]
	ds_read_b128 v[198:201], v100 offset:34816
	ds_read_b128 v[202:205], v100 offset:35840
	s_waitcnt lgkmcnt(4)
	v_mfma_f32_16x16x32_bf16 v[36:39], v[76:79], v[214:217], v[36:39]
	v_mfma_f32_16x16x32_bf16 v[32:35], v[92:95], v[214:217], v[32:35]
	v_mfma_f32_16x16x32_bf16 v[36:39], v[84:87], v[218:221], v[36:39]
	v_mfma_f32_16x16x32_bf16 v[32:35], v[96:99], v[218:221], v[32:35]
	ds_read_b128 v[206:209], v100 offset:36864
	ds_read_b128 v[210:213], v100 offset:37888
	s_waitcnt lgkmcnt(4)
	v_mfma_f32_16x16x32_bf16 v[28:31], v[76:79], v[80:83], v[28:31]
	v_mfma_f32_16x16x32_bf16 v[24:27], v[92:95], v[80:83], v[24:27]
	v_mfma_f32_16x16x32_bf16 v[28:31], v[84:87], v[88:91], v[28:31]
	v_mfma_f32_16x16x32_bf16 v[24:27], v[96:99], v[88:91], v[24:27]
	ds_read_b128 v[214:217], v100 offset:38912
	ds_read_b128 v[218:221], v100 offset:39936
	s_waitcnt lgkmcnt(4)
	v_mfma_f32_16x16x32_bf16 v[20:23], v[76:79], v[198:201], v[20:23]
	v_mfma_f32_16x16x32_bf16 v[16:19], v[92:95], v[198:201], v[16:19]
	v_mfma_f32_16x16x32_bf16 v[20:23], v[84:87], v[202:205], v[20:23]
	v_mfma_f32_16x16x32_bf16 v[16:19], v[96:99], v[202:205], v[16:19]
	s_waitcnt lgkmcnt(2)
	v_mfma_f32_16x16x32_bf16 v[12:15], v[76:79], v[206:209], v[12:15]
	v_mfma_f32_16x16x32_bf16 v[8:11], v[92:95], v[206:209], v[8:11]
	v_mfma_f32_16x16x32_bf16 v[12:15], v[84:87], v[210:213], v[12:15]
	v_mfma_f32_16x16x32_bf16 v[8:11], v[96:99], v[210:213], v[8:11]
	s_waitcnt vmcnt(0)
	s_waitcnt vmcnt(0) lgkmcnt(0)
	v_mfma_f32_16x16x32_bf16 v[4:7], v[76:79], v[214:217], v[4:7]
	s_barrier
	v_mfma_f32_16x16x32_bf16 v[0:3], v[92:95], v[214:217], v[0:3]
	v_mfma_f32_16x16x32_bf16 v[4:7], v[84:87], v[218:221], v[4:7]
	v_mfma_f32_16x16x32_bf16 v[0:3], v[96:99], v[218:221], v[0:3]
	s_cbranch_scc0 .LBB0_903

.LBB0_983:
	s_or_b64 exec, exec, s[6:7]
	v_lshlrev_b32_e32 v6, 16, v2
	v_and_b32_e32 v2, 0xffff0000, v2
	v_mul_f32_e32 v8, v58, v2
	v_lshlrev_b32_e32 v7, 16, v3
	v_fmac_f32_e32 v8, v57, v6
	v_mul_f32_e32 v5, v57, v5
	v_fmac_f32_e32 v8, v59, v7
	v_fmac_f32_e32 v5, v58, v6
	v_add_f32_e32 v6, v60, v8
	v_mul_f32_e32 v8, v58, v7
	v_and_b32_e32 v3, 0xffff0000, v3
	v_fmac_f32_e32 v8, v57, v2
	v_fmac_f32_e32 v8, v59, v3
	v_mul_f32_e32 v3, v58, v3
	v_fmac_f32_e32 v3, v57, v7
	v_fmac_f32_e32 v3, v59, v4
	s_waitcnt lgkmcnt(0)
	v_lshlrev_b32_e32 v4, 16, v0
	v_and_b32_e32 v0, 0xffff0000, v0
	s_xor_b64 s[6:7], s[44:45], -1
	v_fmac_f32_e32 v5, v59, v2
	v_fmac_f32_e32 v13, v56, v0
	v_lshlrev_b32_e32 v0, 16, v1
	v_add_f32_e32 v5, v60, v5
	v_fmac_f32_e32 v12, v56, v4
	v_fmac_f32_e32 v14, v56, v0
	v_and_b32_e32 v0, 0xffff0000, v1
	s_andn2_b64 s[36:37], s[40:41], exec
	s_and_b64 s[6:7], s[6:7], exec
	v_add_f32_e32 v2, v60, v8
	v_add_f32_e32 v3, v60, v3
	v_fmac_f32_e32 v15, v56, v0
	v_mul_f32_e32 v0, v12, v5
	v_mul_f32_e32 v1, v13, v6
	s_or_b64 s[40:41], s[36:37], s[6:7]
	v_mul_f32_e32 v2, v14, v2
	v_mul_f32_e32 v3, v15, v3
	v_cvt_pk_bf16_f32 v0, v0, v1
	v_cvt_pk_bf16_f32 v1, v2, v3
	global_store_dwordx2 v[16:17], v[0:1], off offset:112

.LBB0_992:
	s_or_b64 exec, exec, s[36:37]
	v_mov_b32_e32 v36, 0x21ca8
	v_or_b32_e32 v34, v34, v46
	v_add_u32_e32 v36, 0, v36
	ds_read_b64 v[36:37], v36
	v_lshl_add_u32 v38, v34, 1, v55
	ds_read_b64 v[38:39], v38
	v_cmp_lt_i32_e64 s[36:37], 0, v34
	v_mov_b32_e32 v61, 0
	s_waitcnt lgkmcnt(1)
	v_readfirstlane_b32 s6, v36
	v_readfirstlane_b32 s7, v37
	s_add_u32 s6, s6, s30
	s_addc_u32 s7, s7, s31
	v_lshlrev_b32_e32 v36, 8, v35
	v_lshl_add_u32 v35, v35, 12, v195
	s_nop 0
	global_load_dword v56, v165, s[6:7]
	global_load_dword v57, v165, s[10:11]
	global_load_dword v58, v165, s[12:13]
	global_load_dword v59, v165, s[14:15]
	global_load_dword v60, v165, s[8:9] offset:2048
	v_cndmask_b32_e32 v164, v35, v36, vcc
	v_mad_u64_u32 v[36:37], s[6:7], v164, s23, v[32:33]
	v_ashrrev_i32_e32 v35, 31, v34
	v_lshl_add_u64 v[36:37], v[34:35], 1, v[36:37]
	global_load_dwordx2 v[198:199], v[36:37], off nt
	global_load_dwordx2 v[200:201], v[36:37], off offset:16 nt
	global_load_dwordx2 v[202:203], v[36:37], off offset:32 nt
	global_load_dwordx2 v[204:205], v[36:37], off offset:48 nt
	global_load_dwordx2 v[206:207], v[36:37], off offset:64 nt
	global_load_dwordx2 v[208:209], v[36:37], off offset:80 nt
	global_load_dwordx2 v[210:211], v[36:37], off offset:96 nt
	global_load_dwordx2 v[212:213], v[36:37], off offset:112 nt
	global_load_ushort v214, v[36:37], off offset:-2
	global_load_ushort v222, v[36:37], off offset:8
	global_load_ushort v215, v[36:37], off offset:14
	global_load_ushort v223, v[36:37], off offset:24
	global_load_ushort v216, v[36:37], off offset:30
	global_load_ushort v224, v[36:37], off offset:40
	global_load_ushort v217, v[36:37], off offset:46
	global_load_ushort v225, v[36:37], off offset:56
	global_load_ushort v218, v[36:37], off offset:62
	global_load_ushort v226, v[36:37], off offset:72
	global_load_ushort v219, v[36:37], off offset:78
	global_load_ushort v227, v[36:37], off offset:88
	global_load_ushort v220, v[36:37], off offset:94
	global_load_ushort v228, v[36:37], off offset:104
	global_load_ushort v221, v[36:37], off offset:110
	global_load_ushort v229, v[36:37], off offset:120
	s_waitcnt vmcnt(0)
	v_mov_b32_e32 v40, v198
	v_mov_b32_e32 v41, v199
	v_mov_b32_e32 v62, 0
	s_and_saveexec_b64 s[6:7], s[36:37]
	s_cbranch_execz .LBB0_994
	v_lshlrev_b32_e32 v62, 16, v214
.LBB0_994:
	s_or_b64 exec, exec, s[6:7]
	v_cmp_gt_i32_e64 s[36:37], s48, v34
	s_and_saveexec_b64 s[6:7], s[36:37]
	s_cbranch_execz .LBB0_996
	v_lshlrev_b32_e32 v61, 16, v222
.LBB0_996:
	s_or_b64 exec, exec, s[6:7]
	v_lshlrev_b32_e32 v63, 16, v40
	v_and_b32_e32 v40, 0xffff0000, v40
	v_mul_f32_e32 v67, v58, v40
	v_lshlrev_b32_e32 v66, 16, v41
	v_fmac_f32_e32 v67, v57, v63
	v_mul_f32_e32 v62, v57, v62
	v_fmac_f32_e32 v67, v59, v66
	v_fmac_f32_e32 v62, v58, v63
	v_add_f32_e32 v63, v60, v67
	v_mul_f32_e32 v67, v58, v66
	v_and_b32_e32 v41, 0xffff0000, v41
	v_fmac_f32_e32 v67, v57, v40
	v_fmac_f32_e32 v67, v59, v41
	v_mul_f32_e32 v41, v58, v41
	v_fmac_f32_e32 v41, v57, v66
	v_fmac_f32_e32 v41, v59, v61
	s_waitcnt lgkmcnt(0)
	v_lshlrev_b32_e32 v61, 16, v38
	v_and_b32_e32 v38, 0xffff0000, v38
	v_fmac_f32_e32 v62, v59, v40
	v_fmac_f32_e32 v17, v56, v38
	v_lshlrev_b32_e32 v38, 16, v39
	v_lshlrev_b64 v[64:65], 10, v[164:165]
	v_add_f32_e32 v62, v60, v62
	v_fmac_f32_e32 v16, v56, v61
	v_fmac_f32_e32 v18, v56, v38
	v_and_b32_e32 v38, 0xffff0000, v39
	v_lshl_add_u64 v[64:65], s[16:17], 0, v[64:65]
	v_add_f32_e32 v40, v60, v67
	v_add_f32_e32 v41, v60, v41
	v_fmac_f32_e32 v19, v56, v38
	v_mul_f32_e32 v16, v16, v62
	v_mul_f32_e32 v17, v17, v63
	v_mul_f32_e32 v38, v18, v40
	v_mul_f32_e32 v19, v19, v41
	v_cvt_pk_bf16_f32 v18, v16, v17
	v_lshl_add_u64 v[16:17], v[34:35], 1, v[64:65]
	v_cvt_pk_bf16_f32 v19, v38, v19
	global_store_dwordx2 v[16:17], v[18:19], off
	v_mov_b32_e32 v38, v200
	v_mov_b32_e32 v39, v201
	v_lshl_add_u32 v35, v34, 1, v55
	ds_read_b64 v[18:19], v35 offset:16
	v_cmp_lt_i32_e64 s[36:37], -1, v54
	v_mov_b32_e32 v40, 0
	v_mov_b32_e32 v41, 0
	s_and_saveexec_b64 s[6:7], s[36:37]
	s_cbranch_execz .LBB0_998
	v_lshlrev_b32_e32 v41, 16, v215
.LBB0_998:
	s_or_b64 exec, exec, s[6:7]
	v_cmp_gt_i32_e64 s[38:39], s2, v34
	s_and_saveexec_b64 s[6:7], s[38:39]
	s_cbranch_execz .LBB0_1000
	v_lshlrev_b32_e32 v40, 16, v223
.LBB0_1000:
	s_or_b64 exec, exec, s[6:7]
	v_lshlrev_b32_e32 v54, 16, v38
	v_and_b32_e32 v38, 0xffff0000, v38
	v_mul_f32_e32 v61, v58, v38
	v_lshlrev_b32_e32 v55, 16, v39
	v_fmac_f32_e32 v61, v57, v54
	v_mul_f32_e32 v41, v57, v41
	v_fmac_f32_e32 v61, v59, v55
	v_fmac_f32_e32 v41, v58, v54
	v_add_f32_e32 v54, v60, v61
	v_mul_f32_e32 v61, v58, v55
	v_and_b32_e32 v39, 0xffff0000, v39
	v_fmac_f32_e32 v61, v57, v38
	v_fmac_f32_e32 v61, v59, v39
	v_mul_f32_e32 v39, v58, v39
	v_fmac_f32_e32 v39, v57, v55
	v_fmac_f32_e32 v39, v59, v40
	s_waitcnt lgkmcnt(0)
	v_lshlrev_b32_e32 v40, 16, v18
	v_and_b32_e32 v18, 0xffff0000, v18
	v_fmac_f32_e32 v41, v59, v38
	v_fmac_f32_e32 v21, v56, v18
	v_lshlrev_b32_e32 v18, 16, v19
	v_add_f32_e32 v41, v60, v41
	v_fmac_f32_e32 v20, v56, v40
	v_fmac_f32_e32 v22, v56, v18
	v_and_b32_e32 v18, 0xffff0000, v19
	v_add_f32_e32 v38, v60, v61
	v_add_f32_e32 v39, v60, v39
	v_fmac_f32_e32 v23, v56, v18
	v_mul_f32_e32 v18, v20, v41
	v_mul_f32_e32 v19, v21, v54
	v_mul_f32_e32 v20, v22, v38
	v_mul_f32_e32 v21, v23, v39
	v_cvt_pk_bf16_f32 v18, v18, v19
	v_cvt_pk_bf16_f32 v19, v20, v21
	global_store_dwordx2 v[16:17], v[18:19], off offset:16
	v_mov_b32_e32 v20, v202
	v_mov_b32_e32 v21, v203
	ds_read_b64 v[18:19], v35 offset:32
	v_mov_b32_e32 v22, 0
	v_mov_b32_e32 v23, 0
	s_and_saveexec_b64 s[6:7], s[36:37]
	s_cbranch_execz .LBB0_1002
	v_lshlrev_b32_e32 v23, 16, v216
.LBB0_1002:
	s_or_b64 exec, exec, s[6:7]
	v_cmp_gt_i32_e64 s[38:39], s22, v34
	s_and_saveexec_b64 s[6:7], s[38:39]
	s_cbranch_execz .LBB0_1004
	v_lshlrev_b32_e32 v22, 16, v224
.LBB0_1004:
	s_or_b64 exec, exec, s[6:7]
	v_lshlrev_b32_e32 v38, 16, v20
	v_and_b32_e32 v20, 0xffff0000, v20
	v_mul_f32_e32 v40, v58, v20
	v_lshlrev_b32_e32 v39, 16, v21
	v_fmac_f32_e32 v40, v57, v38
	v_mul_f32_e32 v23, v57, v23
	v_fmac_f32_e32 v40, v59, v39
	v_fmac_f32_e32 v23, v58, v38
	v_add_f32_e32 v38, v60, v40
	v_mul_f32_e32 v40, v58, v39
	v_and_b32_e32 v21, 0xffff0000, v21
	v_fmac_f32_e32 v40, v57, v20
	v_fmac_f32_e32 v40, v59, v21
	v_mul_f32_e32 v21, v58, v21
	v_fmac_f32_e32 v21, v57, v39
	v_fmac_f32_e32 v21, v59, v22
	s_waitcnt lgkmcnt(0)
	v_lshlrev_b32_e32 v22, 16, v18
	v_and_b32_e32 v18, 0xffff0000, v18
	v_fmac_f32_e32 v23, v59, v20
	v_fmac_f32_e32 v25, v56, v18
	v_lshlrev_b32_e32 v18, 16, v19
	v_add_f32_e32 v23, v60, v23
	v_fmac_f32_e32 v24, v56, v22
	v_fmac_f32_e32 v26, v56, v18
	v_and_b32_e32 v18, 0xffff0000, v19
	v_add_f32_e32 v20, v60, v40
	v_add_f32_e32 v21, v60, v21
	v_fmac_f32_e32 v27, v56, v18
	v_mul_f32_e32 v18, v24, v23
	v_mul_f32_e32 v19, v25, v38
	v_mul_f32_e32 v20, v26, v20
	v_mul_f32_e32 v21, v27, v21
	v_cvt_pk_bf16_f32 v18, v18, v19
	v_cvt_pk_bf16_f32 v19, v20, v21
	global_store_dwordx2 v[16:17], v[18:19], off offset:32
	v_mov_b32_e32 v20, v204
	v_mov_b32_e32 v21, v205
	ds_read_b64 v[18:19], v35 offset:48
	v_mov_b32_e32 v22, 0
	v_mov_b32_e32 v23, 0
	s_and_saveexec_b64 s[6:7], s[36:37]
	s_cbranch_execz .LBB0_1006
	v_lshlrev_b32_e32 v23, 16, v217
.LBB0_1006:
	s_or_b64 exec, exec, s[6:7]
	v_cmp_gt_i32_e64 s[38:39], s25, v34
	s_and_saveexec_b64 s[6:7], s[38:39]
	s_cbranch_execz .LBB0_1008
	v_lshlrev_b32_e32 v22, 16, v225
.LBB0_1008:
	s_or_b64 exec, exec, s[6:7]
	v_lshlrev_b32_e32 v24, 16, v20
	v_and_b32_e32 v20, 0xffff0000, v20
	v_mul_f32_e32 v26, v58, v20
	v_lshlrev_b32_e32 v25, 16, v21
	v_fmac_f32_e32 v26, v57, v24
	v_mul_f32_e32 v23, v57, v23
	v_fmac_f32_e32 v26, v59, v25
	v_fmac_f32_e32 v23, v58, v24
	v_add_f32_e32 v24, v60, v26
	v_mul_f32_e32 v26, v58, v25
	v_and_b32_e32 v21, 0xffff0000, v21
	v_fmac_f32_e32 v26, v57, v20
	v_fmac_f32_e32 v26, v59, v21
	v_mul_f32_e32 v21, v58, v21
	v_fmac_f32_e32 v21, v57, v25
	v_fmac_f32_e32 v21, v59, v22
	s_waitcnt lgkmcnt(0)
	v_lshlrev_b32_e32 v22, 16, v18
	v_and_b32_e32 v18, 0xffff0000, v18
	v_fmac_f32_e32 v23, v59, v20
	v_fmac_f32_e32 v29, v56, v18
	v_lshlrev_b32_e32 v18, 16, v19
	v_add_f32_e32 v23, v60, v23
	v_fmac_f32_e32 v28, v56, v22
	v_fmac_f32_e32 v30, v56, v18
	v_and_b32_e32 v18, 0xffff0000, v19
	v_add_f32_e32 v20, v60, v26
	v_add_f32_e32 v21, v60, v21
	v_fmac_f32_e32 v31, v56, v18
	v_mul_f32_e32 v18, v28, v23
	v_mul_f32_e32 v19, v29, v24
	v_mul_f32_e32 v20, v30, v20
	v_mul_f32_e32 v21, v31, v21
	v_cvt_pk_bf16_f32 v18, v18, v19
	v_cvt_pk_bf16_f32 v19, v20, v21
	global_store_dwordx2 v[16:17], v[18:19], off offset:48
	v_mov_b32_e32 v20, v206
	v_mov_b32_e32 v21, v207
	ds_read_b64 v[18:19], v35 offset:64
	v_mov_b32_e32 v22, 0
	v_mov_b32_e32 v23, 0
	s_and_saveexec_b64 s[6:7], s[36:37]
	s_cbranch_execz .LBB0_1010
	v_lshlrev_b32_e32 v23, 16, v218
.LBB0_1010:
	s_or_b64 exec, exec, s[6:7]
	v_cmp_gt_i32_e64 s[38:39], s27, v34
	s_and_saveexec_b64 s[6:7], s[38:39]
	s_cbranch_execz .LBB0_1012
	v_lshlrev_b32_e32 v22, 16, v226
.LBB0_1012:
	s_or_b64 exec, exec, s[6:7]
	v_lshlrev_b32_e32 v24, 16, v20
	v_and_b32_e32 v20, 0xffff0000, v20
	v_mul_f32_e32 v26, v58, v20
	v_lshlrev_b32_e32 v25, 16, v21
	v_fmac_f32_e32 v26, v57, v24
	v_mul_f32_e32 v23, v57, v23
	v_fmac_f32_e32 v26, v59, v25
	v_fmac_f32_e32 v23, v58, v24
	v_add_f32_e32 v24, v60, v26
	v_mul_f32_e32 v26, v58, v25
	v_and_b32_e32 v21, 0xffff0000, v21
	v_fmac_f32_e32 v26, v57, v20
	v_fmac_f32_e32 v26, v59, v21
	v_mul_f32_e32 v21, v58, v21
	v_fmac_f32_e32 v21, v57, v25
	v_fmac_f32_e32 v21, v59, v22
	s_waitcnt lgkmcnt(0)
	v_lshlrev_b32_e32 v22, 16, v18
	v_and_b32_e32 v18, 0xffff0000, v18
	v_fmac_f32_e32 v23, v59, v20
	v_fmac_f32_e32 v1, v56, v18
	v_lshlrev_b32_e32 v18, 16, v19
	v_add_f32_e32 v23, v60, v23
	v_fmac_f32_e32 v0, v56, v22
	v_fmac_f32_e32 v2, v56, v18
	v_and_b32_e32 v18, 0xffff0000, v19
	v_add_f32_e32 v20, v60, v26
	v_add_f32_e32 v21, v60, v21
	v_fmac_f32_e32 v3, v56, v18
	v_mul_f32_e32 v0, v0, v23
	v_mul_f32_e32 v1, v1, v24
	v_mul_f32_e32 v2, v2, v20
	v_mul_f32_e32 v3, v3, v21
	v_cvt_pk_bf16_f32 v0, v0, v1
	v_cvt_pk_bf16_f32 v1, v2, v3
	global_store_dwordx2 v[16:17], v[0:1], off offset:64
	v_mov_b32_e32 v2, v208
	v_mov_b32_e32 v3, v209
	ds_read_b64 v[0:1], v35 offset:80
	v_mov_b32_e32 v18, 0
	v_mov_b32_e32 v19, 0
	s_and_saveexec_b64 s[6:7], s[36:37]
	s_cbranch_execz .LBB0_1014
	v_lshlrev_b32_e32 v19, 16, v219
.LBB0_1014:
	s_or_b64 exec, exec, s[6:7]
	v_cmp_gt_i32_e64 s[38:39], s0, v34
	s_and_saveexec_b64 s[6:7], s[38:39]
	s_cbranch_execz .LBB0_1016
	v_lshlrev_b32_e32 v18, 16, v227
.LBB0_1016:
	s_or_b64 exec, exec, s[6:7]
	v_lshlrev_b32_e32 v20, 16, v2
	v_and_b32_e32 v2, 0xffff0000, v2
	v_mul_f32_e32 v22, v58, v2
	v_lshlrev_b32_e32 v21, 16, v3
	v_fmac_f32_e32 v22, v57, v20
	v_mul_f32_e32 v19, v57, v19
	v_fmac_f32_e32 v22, v59, v21
	v_fmac_f32_e32 v19, v58, v20
	v_add_f32_e32 v20, v60, v22
	v_mul_f32_e32 v22, v58, v21
	v_and_b32_e32 v3, 0xffff0000, v3
	v_fmac_f32_e32 v22, v57, v2
	v_fmac_f32_e32 v22, v59, v3
	v_mul_f32_e32 v3, v58, v3
	v_fmac_f32_e32 v3, v57, v21
	v_fmac_f32_e32 v3, v59, v18
	s_waitcnt lgkmcnt(0)
	v_lshlrev_b32_e32 v18, 16, v0
	v_and_b32_e32 v0, 0xffff0000, v0
	v_fmac_f32_e32 v19, v59, v2
	v_fmac_f32_e32 v5, v56, v0
	v_lshlrev_b32_e32 v0, 16, v1
	v_add_f32_e32 v19, v60, v19
	v_fmac_f32_e32 v4, v56, v18
	v_fmac_f32_e32 v6, v56, v0
	v_and_b32_e32 v0, 0xffff0000, v1
	v_add_f32_e32 v2, v60, v22
	v_add_f32_e32 v3, v60, v3
	v_fmac_f32_e32 v7, v56, v0
	v_mul_f32_e32 v0, v4, v19
	v_mul_f32_e32 v1, v5, v20
	v_mul_f32_e32 v2, v6, v2
	v_mul_f32_e32 v3, v7, v3
	v_cvt_pk_bf16_f32 v0, v0, v1
	v_cvt_pk_bf16_f32 v1, v2, v3
	global_store_dwordx2 v[16:17], v[0:1], off offset:80
	v_mov_b32_e32 v2, v210
	v_mov_b32_e32 v3, v211
	ds_read_b64 v[0:1], v35 offset:96
	v_mov_b32_e32 v4, 0
	v_mov_b32_e32 v5, 0
	s_and_saveexec_b64 s[6:7], s[36:37]
	s_cbranch_execz .LBB0_1018
	v_lshlrev_b32_e32 v5, 16, v220
.LBB0_1018:
	s_or_b64 exec, exec, s[6:7]
	v_cmp_gt_i32_e64 s[38:39], s1, v34
	s_and_saveexec_b64 s[6:7], s[38:39]
	s_cbranch_execz .LBB0_1020
	v_lshlrev_b32_e32 v4, 16, v228
.LBB0_1020:
	s_or_b64 exec, exec, s[6:7]
	v_lshlrev_b32_e32 v6, 16, v2
	v_and_b32_e32 v2, 0xffff0000, v2
	v_mul_f32_e32 v18, v58, v2
	v_lshlrev_b32_e32 v7, 16, v3
	v_fmac_f32_e32 v18, v57, v6
	v_mul_f32_e32 v5, v57, v5
	v_fmac_f32_e32 v18, v59, v7
	v_fmac_f32_e32 v5, v58, v6
	v_add_f32_e32 v6, v60, v18
	v_mul_f32_e32 v18, v58, v7
	v_and_b32_e32 v3, 0xffff0000, v3
	v_fmac_f32_e32 v18, v57, v2
	v_fmac_f32_e32 v18, v59, v3
	v_mul_f32_e32 v3, v58, v3
	v_fmac_f32_e32 v3, v57, v7
	v_fmac_f32_e32 v3, v59, v4
	s_waitcnt lgkmcnt(0)
	v_lshlrev_b32_e32 v4, 16, v0
	v_and_b32_e32 v0, 0xffff0000, v0
	v_fmac_f32_e32 v5, v59, v2
	v_fmac_f32_e32 v9, v56, v0
	v_lshlrev_b32_e32 v0, 16, v1
	v_add_f32_e32 v5, v60, v5
	v_fmac_f32_e32 v8, v56, v4
	v_fmac_f32_e32 v10, v56, v0
	v_and_b32_e32 v0, 0xffff0000, v1
	v_add_f32_e32 v2, v60, v18
	v_add_f32_e32 v3, v60, v3
	v_fmac_f32_e32 v11, v56, v0
	v_mul_f32_e32 v0, v8, v5
	v_mul_f32_e32 v1, v9, v6
	v_mul_f32_e32 v2, v10, v2
	v_mul_f32_e32 v3, v11, v3
	v_cvt_pk_bf16_f32 v0, v0, v1
	v_cvt_pk_bf16_f32 v1, v2, v3
	global_store_dwordx2 v[16:17], v[0:1], off offset:96
	v_mov_b32_e32 v2, v212
	v_mov_b32_e32 v3, v213
	ds_read_b64 v[0:1], v35 offset:112
	v_mov_b32_e32 v4, 0
	v_mov_b32_e32 v5, 0
	s_and_saveexec_b64 s[6:7], s[36:37]
	s_cbranch_execz .LBB0_1022
	v_lshlrev_b32_e32 v5, 16, v221
.LBB0_1022:
	s_or_b64 exec, exec, s[6:7]
	v_cmp_gt_i32_e64 s[36:37], s34, v34
	s_and_saveexec_b64 s[6:7], s[36:37]
	s_cbranch_execz .LBB0_983
	v_lshlrev_b32_e32 v4, 16, v229
	s_branch .LBB0_983

.LBB0_1025:
	s_barrier
	s_waitcnt vmcnt(0)
	v_mov_b32_e32 v0, v188
	s_barrier
	s_nop 0
	v_cmp_eq_u32_e32 vcc, 0, v0
	s_and_saveexec_b64 s[4:5], vcc
	v_readlane_b32 s22, v238, 28
	s_branch .LBB0_1077

.LBB0_1097:
	s_or_b64 exec, exec, s[6:7]
	v_lshlrev_b32_e32 v6, 16, v2
	v_and_b32_e32 v2, 0xffff0000, v2
	v_mul_f32_e32 v8, v60, v2
	v_lshlrev_b32_e32 v7, 16, v3
	v_fmac_f32_e32 v8, v59, v6
	v_mul_f32_e32 v5, v59, v5
	v_fmac_f32_e32 v8, v61, v7
	v_fmac_f32_e32 v5, v60, v6
	v_add_f32_e32 v6, v62, v8
	v_mul_f32_e32 v8, v60, v7
	v_and_b32_e32 v3, 0xffff0000, v3
	v_fmac_f32_e32 v8, v59, v2
	v_fmac_f32_e32 v8, v61, v3
	v_mul_f32_e32 v3, v60, v3
	v_fmac_f32_e32 v3, v59, v7
	v_fmac_f32_e32 v3, v61, v4
	s_waitcnt lgkmcnt(0)
	v_lshlrev_b32_e32 v4, 16, v0
	v_and_b32_e32 v0, 0xffff0000, v0
	s_xor_b64 s[6:7], s[42:43], -1
	v_fmac_f32_e32 v5, v61, v2
	v_fmac_f32_e32 v13, v58, v0
	v_lshlrev_b32_e32 v0, 16, v1
	v_add_f32_e32 v5, v62, v5
	v_fmac_f32_e32 v12, v58, v4
	v_fmac_f32_e32 v14, v58, v0
	v_and_b32_e32 v0, 0xffff0000, v1
	s_andn2_b64 s[34:35], s[38:39], exec
	s_and_b64 s[6:7], s[6:7], exec
	v_add_f32_e32 v2, v62, v8
	v_add_f32_e32 v3, v62, v3
	v_fmac_f32_e32 v15, v58, v0
	v_mul_f32_e32 v0, v12, v5
	v_mul_f32_e32 v1, v13, v6
	s_or_b64 s[38:39], s[34:35], s[6:7]
	v_mul_f32_e32 v2, v14, v2
	v_mul_f32_e32 v3, v15, v3
	v_cvt_pk_bf16_f32 v0, v0, v1
	v_cvt_pk_bf16_f32 v1, v2, v3
	global_store_dwordx2 v[16:17], v[0:1], off offset:112

.LBB0_1106:
	s_or_b64 exec, exec, s[34:35]
	v_mov_b32_e32 v38, 0x21ca8
	v_or_b32_e32 v36, v36, v48
	v_add_u32_e32 v38, 0, v38
	ds_read_b64 v[38:39], v38
	v_lshl_add_u32 v40, v36, 1, v57
	ds_read_b64 v[40:41], v40
	v_cmp_lt_i32_e64 s[34:35], 0, v36
	v_mov_b32_e32 v63, 0
	s_waitcnt lgkmcnt(1)
	v_readfirstlane_b32 s6, v38
	v_readfirstlane_b32 s7, v39
	s_add_u32 s6, s6, s30
	s_addc_u32 s7, s7, s31
	v_lshlrev_b32_e32 v38, 8, v37
	v_lshl_add_u32 v37, v37, 12, v195
	s_nop 0
	global_load_dword v58, v165, s[6:7] offset:2048
	global_load_dword v59, v165, s[10:11]
	global_load_dword v60, v165, s[12:13]
	global_load_dword v61, v165, s[14:15]
	global_load_dword v62, v165, s[16:17]
	v_cndmask_b32_e32 v164, v37, v38, vcc
	v_mad_u64_u32 v[38:39], s[6:7], v164, s23, v[32:33]
	v_ashrrev_i32_e32 v37, 31, v36
	v_lshl_add_u64 v[38:39], v[36:37], 1, v[38:39]
	global_load_dwordx2 v[198:199], v[38:39], off nt
	global_load_dwordx2 v[200:201], v[38:39], off offset:16 nt
	global_load_dwordx2 v[202:203], v[38:39], off offset:32 nt
	global_load_dwordx2 v[204:205], v[38:39], off offset:48 nt
	global_load_dwordx2 v[206:207], v[38:39], off offset:64 nt
	global_load_dwordx2 v[208:209], v[38:39], off offset:80 nt
	global_load_dwordx2 v[210:211], v[38:39], off offset:96 nt
	global_load_dwordx2 v[212:213], v[38:39], off offset:112 nt
	global_load_ushort v214, v[38:39], off offset:-2
	global_load_ushort v222, v[38:39], off offset:8
	global_load_ushort v215, v[38:39], off offset:14
	global_load_ushort v223, v[38:39], off offset:24
	global_load_ushort v216, v[38:39], off offset:30
	global_load_ushort v224, v[38:39], off offset:40
	global_load_ushort v217, v[38:39], off offset:46
	global_load_ushort v225, v[38:39], off offset:56
	global_load_ushort v218, v[38:39], off offset:62
	global_load_ushort v226, v[38:39], off offset:72
	global_load_ushort v219, v[38:39], off offset:78
	global_load_ushort v227, v[38:39], off offset:88
	global_load_ushort v220, v[38:39], off offset:94
	global_load_ushort v228, v[38:39], off offset:104
	global_load_ushort v221, v[38:39], off offset:110
	global_load_ushort v229, v[38:39], off offset:120
	s_waitcnt vmcnt(0)
	v_mov_b32_e32 v42, v198
	v_mov_b32_e32 v43, v199
	v_mov_b32_e32 v64, 0
	s_and_saveexec_b64 s[6:7], s[34:35]
	s_cbranch_execz .LBB0_1108
	v_lshlrev_b32_e32 v64, 16, v214
.LBB0_1108:
	s_or_b64 exec, exec, s[6:7]
	v_cmp_gt_i32_e64 s[34:35], s81, v36
	s_and_saveexec_b64 s[6:7], s[34:35]
	s_cbranch_execz .LBB0_1110
	v_lshlrev_b32_e32 v63, 16, v222
.LBB0_1110:
	s_or_b64 exec, exec, s[6:7]
	v_lshlrev_b32_e32 v65, 16, v42
	v_and_b32_e32 v42, 0xffff0000, v42
	v_mul_f32_e32 v69, v60, v42
	v_lshlrev_b32_e32 v68, 16, v43
	v_fmac_f32_e32 v69, v59, v65
	v_mul_f32_e32 v64, v59, v64
	v_fmac_f32_e32 v69, v61, v68
	v_fmac_f32_e32 v64, v60, v65
	v_add_f32_e32 v65, v62, v69
	v_mul_f32_e32 v69, v60, v68
	v_and_b32_e32 v43, 0xffff0000, v43
	v_fmac_f32_e32 v69, v59, v42
	v_fmac_f32_e32 v69, v61, v43
	v_mul_f32_e32 v43, v60, v43
	v_fmac_f32_e32 v43, v59, v68
	v_fmac_f32_e32 v43, v61, v63
	s_waitcnt lgkmcnt(0)
	v_lshlrev_b32_e32 v63, 16, v40
	v_and_b32_e32 v40, 0xffff0000, v40
	v_fmac_f32_e32 v64, v61, v42
	v_fmac_f32_e32 v17, v58, v40
	v_lshlrev_b32_e32 v40, 16, v41
	v_lshlrev_b64 v[66:67], 10, v[164:165]
	v_add_f32_e32 v64, v62, v64
	v_fmac_f32_e32 v16, v58, v63
	v_fmac_f32_e32 v18, v58, v40
	v_and_b32_e32 v40, 0xffff0000, v41
	v_lshl_add_u64 v[66:67], v[34:35], 0, v[66:67]
	v_add_f32_e32 v42, v62, v69
	v_add_f32_e32 v43, v62, v43
	v_fmac_f32_e32 v19, v58, v40
	v_mul_f32_e32 v16, v16, v64
	v_mul_f32_e32 v17, v17, v65
	v_mul_f32_e32 v40, v18, v42
	v_mul_f32_e32 v19, v19, v43
	v_cvt_pk_bf16_f32 v18, v16, v17
	v_lshl_add_u64 v[16:17], v[36:37], 1, v[66:67]
	v_cvt_pk_bf16_f32 v19, v40, v19
	global_store_dwordx2 v[16:17], v[18:19], off
	v_mov_b32_e32 v40, v200
	v_mov_b32_e32 v41, v201
	v_lshl_add_u32 v37, v36, 1, v57
	ds_read_b64 v[18:19], v37 offset:16
	v_cmp_lt_i32_e64 s[34:35], -1, v56
	v_mov_b32_e32 v42, 0
	v_mov_b32_e32 v43, 0
	s_and_saveexec_b64 s[6:7], s[34:35]
	s_cbranch_execz .LBB0_1112
	v_lshlrev_b32_e32 v43, 16, v215
.LBB0_1112:
	s_or_b64 exec, exec, s[6:7]
	v_cmp_gt_i32_e64 s[36:37], s82, v36
	s_and_saveexec_b64 s[6:7], s[36:37]
	s_cbranch_execz .LBB0_1114
	v_lshlrev_b32_e32 v42, 16, v223
.LBB0_1114:
	s_or_b64 exec, exec, s[6:7]
	v_lshlrev_b32_e32 v56, 16, v40
	v_and_b32_e32 v40, 0xffff0000, v40
	v_mul_f32_e32 v63, v60, v40
	v_lshlrev_b32_e32 v57, 16, v41
	v_fmac_f32_e32 v63, v59, v56
	v_mul_f32_e32 v43, v59, v43
	v_fmac_f32_e32 v63, v61, v57
	v_fmac_f32_e32 v43, v60, v56
	v_add_f32_e32 v56, v62, v63
	v_mul_f32_e32 v63, v60, v57
	v_and_b32_e32 v41, 0xffff0000, v41
	v_fmac_f32_e32 v63, v59, v40
	v_fmac_f32_e32 v63, v61, v41
	v_mul_f32_e32 v41, v60, v41
	v_fmac_f32_e32 v41, v59, v57
	v_fmac_f32_e32 v41, v61, v42
	s_waitcnt lgkmcnt(0)
	v_lshlrev_b32_e32 v42, 16, v18
	v_and_b32_e32 v18, 0xffff0000, v18
	v_fmac_f32_e32 v43, v61, v40
	v_fmac_f32_e32 v21, v58, v18
	v_lshlrev_b32_e32 v18, 16, v19
	v_add_f32_e32 v43, v62, v43
	v_fmac_f32_e32 v20, v58, v42
	v_fmac_f32_e32 v22, v58, v18
	v_and_b32_e32 v18, 0xffff0000, v19
	v_add_f32_e32 v40, v62, v63
	v_add_f32_e32 v41, v62, v41
	v_fmac_f32_e32 v23, v58, v18
	v_mul_f32_e32 v18, v20, v43
	v_mul_f32_e32 v19, v21, v56
	v_mul_f32_e32 v20, v22, v40
	v_mul_f32_e32 v21, v23, v41
	v_cvt_pk_bf16_f32 v18, v18, v19
	v_cvt_pk_bf16_f32 v19, v20, v21
	global_store_dwordx2 v[16:17], v[18:19], off offset:16
	v_mov_b32_e32 v20, v202
	v_mov_b32_e32 v21, v203
	ds_read_b64 v[18:19], v37 offset:32
	v_mov_b32_e32 v22, 0
	v_mov_b32_e32 v23, 0
	s_and_saveexec_b64 s[6:7], s[34:35]
	s_cbranch_execz .LBB0_1116
	v_lshlrev_b32_e32 v23, 16, v216
.LBB0_1116:
	s_or_b64 exec, exec, s[6:7]
	v_cmp_gt_i32_e64 s[36:37], s83, v36
	s_and_saveexec_b64 s[6:7], s[36:37]
	s_cbranch_execz .LBB0_1118
	v_lshlrev_b32_e32 v22, 16, v224
.LBB0_1118:
	s_or_b64 exec, exec, s[6:7]
	v_lshlrev_b32_e32 v40, 16, v20
	v_and_b32_e32 v20, 0xffff0000, v20
	v_mul_f32_e32 v42, v60, v20
	v_lshlrev_b32_e32 v41, 16, v21
	v_fmac_f32_e32 v42, v59, v40
	v_mul_f32_e32 v23, v59, v23
	v_fmac_f32_e32 v42, v61, v41
	v_fmac_f32_e32 v23, v60, v40
	v_add_f32_e32 v40, v62, v42
	v_mul_f32_e32 v42, v60, v41
	v_and_b32_e32 v21, 0xffff0000, v21
	v_fmac_f32_e32 v42, v59, v20
	v_fmac_f32_e32 v42, v61, v21
	v_mul_f32_e32 v21, v60, v21
	v_fmac_f32_e32 v21, v59, v41
	v_fmac_f32_e32 v21, v61, v22
	s_waitcnt lgkmcnt(0)
	v_lshlrev_b32_e32 v22, 16, v18
	v_and_b32_e32 v18, 0xffff0000, v18
	v_fmac_f32_e32 v23, v61, v20
	v_fmac_f32_e32 v25, v58, v18
	v_lshlrev_b32_e32 v18, 16, v19
	v_add_f32_e32 v23, v62, v23
	v_fmac_f32_e32 v24, v58, v22
	v_fmac_f32_e32 v26, v58, v18
	v_and_b32_e32 v18, 0xffff0000, v19
	v_add_f32_e32 v20, v62, v42
	v_add_f32_e32 v21, v62, v21
	v_fmac_f32_e32 v27, v58, v18
	v_mul_f32_e32 v18, v24, v23
	v_mul_f32_e32 v19, v25, v40
	v_mul_f32_e32 v20, v26, v20
	v_mul_f32_e32 v21, v27, v21
	v_cvt_pk_bf16_f32 v18, v18, v19
	v_cvt_pk_bf16_f32 v19, v20, v21
	global_store_dwordx2 v[16:17], v[18:19], off offset:32
	v_mov_b32_e32 v20, v204
	v_mov_b32_e32 v21, v205
	ds_read_b64 v[18:19], v37 offset:48
	v_mov_b32_e32 v22, 0
	v_mov_b32_e32 v23, 0
	s_and_saveexec_b64 s[6:7], s[34:35]
	s_cbranch_execz .LBB0_1120
	v_lshlrev_b32_e32 v23, 16, v217
.LBB0_1120:
	s_or_b64 exec, exec, s[6:7]
	v_cmp_gt_i32_e64 s[36:37], s84, v36
	s_and_saveexec_b64 s[6:7], s[36:37]
	s_cbranch_execz .LBB0_1122
	v_lshlrev_b32_e32 v22, 16, v225
.LBB0_1122:
	s_or_b64 exec, exec, s[6:7]
	v_lshlrev_b32_e32 v24, 16, v20
	v_and_b32_e32 v20, 0xffff0000, v20
	v_mul_f32_e32 v26, v60, v20
	v_lshlrev_b32_e32 v25, 16, v21
	v_fmac_f32_e32 v26, v59, v24
	v_mul_f32_e32 v23, v59, v23
	v_fmac_f32_e32 v26, v61, v25
	v_fmac_f32_e32 v23, v60, v24
	v_add_f32_e32 v24, v62, v26
	v_mul_f32_e32 v26, v60, v25
	v_and_b32_e32 v21, 0xffff0000, v21
	v_fmac_f32_e32 v26, v59, v20
	v_fmac_f32_e32 v26, v61, v21
	v_mul_f32_e32 v21, v60, v21
	v_fmac_f32_e32 v21, v59, v25
	v_fmac_f32_e32 v21, v61, v22
	s_waitcnt lgkmcnt(0)
	v_lshlrev_b32_e32 v22, 16, v18
	v_and_b32_e32 v18, 0xffff0000, v18
	v_fmac_f32_e32 v23, v61, v20
	v_fmac_f32_e32 v29, v58, v18
	v_lshlrev_b32_e32 v18, 16, v19
	v_add_f32_e32 v23, v62, v23
	v_fmac_f32_e32 v28, v58, v22
	v_fmac_f32_e32 v30, v58, v18
	v_and_b32_e32 v18, 0xffff0000, v19
	v_add_f32_e32 v20, v62, v26
	v_add_f32_e32 v21, v62, v21
	v_fmac_f32_e32 v31, v58, v18
	v_mul_f32_e32 v18, v28, v23
	v_mul_f32_e32 v19, v29, v24
	v_mul_f32_e32 v20, v30, v20
	v_mul_f32_e32 v21, v31, v21
	v_cvt_pk_bf16_f32 v18, v18, v19
	v_cvt_pk_bf16_f32 v19, v20, v21
	global_store_dwordx2 v[16:17], v[18:19], off offset:48
	v_mov_b32_e32 v20, v206
	v_mov_b32_e32 v21, v207
	ds_read_b64 v[18:19], v37 offset:64
	v_mov_b32_e32 v22, 0
	v_mov_b32_e32 v23, 0
	s_and_saveexec_b64 s[6:7], s[34:35]
	s_cbranch_execz .LBB0_1124
	v_lshlrev_b32_e32 v23, 16, v218
.LBB0_1124:
	s_or_b64 exec, exec, s[6:7]
	v_cmp_gt_i32_e64 s[36:37], s85, v36
	s_and_saveexec_b64 s[6:7], s[36:37]
	s_cbranch_execz .LBB0_1126
	v_lshlrev_b32_e32 v22, 16, v226
.LBB0_1126:
	s_or_b64 exec, exec, s[6:7]
	v_lshlrev_b32_e32 v24, 16, v20
	v_and_b32_e32 v20, 0xffff0000, v20
	v_mul_f32_e32 v26, v60, v20
	v_lshlrev_b32_e32 v25, 16, v21
	v_fmac_f32_e32 v26, v59, v24
	v_mul_f32_e32 v23, v59, v23
	v_fmac_f32_e32 v26, v61, v25
	v_fmac_f32_e32 v23, v60, v24
	v_add_f32_e32 v24, v62, v26
	v_mul_f32_e32 v26, v60, v25
	v_and_b32_e32 v21, 0xffff0000, v21
	v_fmac_f32_e32 v26, v59, v20
	v_fmac_f32_e32 v26, v61, v21
	v_mul_f32_e32 v21, v60, v21
	v_fmac_f32_e32 v21, v59, v25
	v_fmac_f32_e32 v21, v61, v22
	s_waitcnt lgkmcnt(0)
	v_lshlrev_b32_e32 v22, 16, v18
	v_and_b32_e32 v18, 0xffff0000, v18
	v_fmac_f32_e32 v23, v61, v20
	v_fmac_f32_e32 v1, v58, v18
	v_lshlrev_b32_e32 v18, 16, v19
	v_add_f32_e32 v23, v62, v23
	v_fmac_f32_e32 v0, v58, v22
	v_fmac_f32_e32 v2, v58, v18
	v_and_b32_e32 v18, 0xffff0000, v19
	v_add_f32_e32 v20, v62, v26
	v_add_f32_e32 v21, v62, v21
	v_fmac_f32_e32 v3, v58, v18
	v_mul_f32_e32 v0, v0, v23
	v_mul_f32_e32 v1, v1, v24
	v_mul_f32_e32 v2, v2, v20
	v_mul_f32_e32 v3, v3, v21
	v_cvt_pk_bf16_f32 v0, v0, v1
	v_cvt_pk_bf16_f32 v1, v2, v3
	global_store_dwordx2 v[16:17], v[0:1], off offset:64
	v_mov_b32_e32 v2, v208
	v_mov_b32_e32 v3, v209
	ds_read_b64 v[0:1], v37 offset:80
	v_mov_b32_e32 v18, 0
	v_mov_b32_e32 v19, 0
	s_and_saveexec_b64 s[6:7], s[34:35]
	s_cbranch_execz .LBB0_1128
	v_lshlrev_b32_e32 v19, 16, v219
.LBB0_1128:
	s_or_b64 exec, exec, s[6:7]
	v_cmp_gt_i32_e64 s[36:37], s0, v36
	s_and_saveexec_b64 s[6:7], s[36:37]
	s_cbranch_execz .LBB0_1130
	v_lshlrev_b32_e32 v18, 16, v227
.LBB0_1130:
	s_or_b64 exec, exec, s[6:7]
	v_lshlrev_b32_e32 v20, 16, v2
	v_and_b32_e32 v2, 0xffff0000, v2
	v_mul_f32_e32 v22, v60, v2
	v_lshlrev_b32_e32 v21, 16, v3
	v_fmac_f32_e32 v22, v59, v20
	v_mul_f32_e32 v19, v59, v19
	v_fmac_f32_e32 v22, v61, v21
	v_fmac_f32_e32 v19, v60, v20
	v_add_f32_e32 v20, v62, v22
	v_mul_f32_e32 v22, v60, v21
	v_and_b32_e32 v3, 0xffff0000, v3
	v_fmac_f32_e32 v22, v59, v2
	v_fmac_f32_e32 v22, v61, v3
	v_mul_f32_e32 v3, v60, v3
	v_fmac_f32_e32 v3, v59, v21
	v_fmac_f32_e32 v3, v61, v18
	s_waitcnt lgkmcnt(0)
	v_lshlrev_b32_e32 v18, 16, v0
	v_and_b32_e32 v0, 0xffff0000, v0
	v_fmac_f32_e32 v19, v61, v2
	v_fmac_f32_e32 v5, v58, v0
	v_lshlrev_b32_e32 v0, 16, v1
	v_add_f32_e32 v19, v62, v19
	v_fmac_f32_e32 v4, v58, v18
	v_fmac_f32_e32 v6, v58, v0
	v_and_b32_e32 v0, 0xffff0000, v1
	v_add_f32_e32 v2, v62, v22
	v_add_f32_e32 v3, v62, v3
	v_fmac_f32_e32 v7, v58, v0
	v_mul_f32_e32 v0, v4, v19
	v_mul_f32_e32 v1, v5, v20
	v_mul_f32_e32 v2, v6, v2
	v_mul_f32_e32 v3, v7, v3
	v_cvt_pk_bf16_f32 v0, v0, v1
	v_cvt_pk_bf16_f32 v1, v2, v3
	global_store_dwordx2 v[16:17], v[0:1], off offset:80
	v_mov_b32_e32 v2, v210
	v_mov_b32_e32 v3, v211
	ds_read_b64 v[0:1], v37 offset:96
	v_mov_b32_e32 v4, 0
	v_mov_b32_e32 v5, 0
	s_and_saveexec_b64 s[6:7], s[34:35]
	s_cbranch_execz .LBB0_1132
	v_lshlrev_b32_e32 v5, 16, v220
.LBB0_1132:
	s_or_b64 exec, exec, s[6:7]
	v_cmp_gt_i32_e64 s[36:37], s1, v36
	s_and_saveexec_b64 s[6:7], s[36:37]
	s_cbranch_execz .LBB0_1134
	v_lshlrev_b32_e32 v4, 16, v228
.LBB0_1134:
	s_or_b64 exec, exec, s[6:7]
	v_lshlrev_b32_e32 v6, 16, v2
	v_and_b32_e32 v2, 0xffff0000, v2
	v_mul_f32_e32 v18, v60, v2
	v_lshlrev_b32_e32 v7, 16, v3
	v_fmac_f32_e32 v18, v59, v6
	v_mul_f32_e32 v5, v59, v5
	v_fmac_f32_e32 v18, v61, v7
	v_fmac_f32_e32 v5, v60, v6
	v_add_f32_e32 v6, v62, v18
	v_mul_f32_e32 v18, v60, v7
	v_and_b32_e32 v3, 0xffff0000, v3
	v_fmac_f32_e32 v18, v59, v2
	v_fmac_f32_e32 v18, v61, v3
	v_mul_f32_e32 v3, v60, v3
	v_fmac_f32_e32 v3, v59, v7
	v_fmac_f32_e32 v3, v61, v4
	s_waitcnt lgkmcnt(0)
	v_lshlrev_b32_e32 v4, 16, v0
	v_and_b32_e32 v0, 0xffff0000, v0
	v_fmac_f32_e32 v5, v61, v2
	v_fmac_f32_e32 v9, v58, v0
	v_lshlrev_b32_e32 v0, 16, v1
	v_add_f32_e32 v5, v62, v5
	v_fmac_f32_e32 v8, v58, v4
	v_fmac_f32_e32 v10, v58, v0
	v_and_b32_e32 v0, 0xffff0000, v1
	v_add_f32_e32 v2, v62, v18
	v_add_f32_e32 v3, v62, v3
	v_fmac_f32_e32 v11, v58, v0
	v_mul_f32_e32 v0, v8, v5
	v_mul_f32_e32 v1, v9, v6
	v_mul_f32_e32 v2, v10, v2
	v_mul_f32_e32 v3, v11, v3
	v_cvt_pk_bf16_f32 v0, v0, v1
	v_cvt_pk_bf16_f32 v1, v2, v3
	global_store_dwordx2 v[16:17], v[0:1], off offset:96
	v_mov_b32_e32 v2, v212
	v_mov_b32_e32 v3, v213
	ds_read_b64 v[0:1], v37 offset:112
	v_mov_b32_e32 v4, 0
	v_mov_b32_e32 v5, 0
	s_and_saveexec_b64 s[6:7], s[34:35]
	s_cbranch_execz .LBB0_1136
	v_lshlrev_b32_e32 v5, 16, v221
.LBB0_1136:
	s_or_b64 exec, exec, s[6:7]
	v_cmp_gt_i32_e64 s[34:35], s64, v36
	s_and_saveexec_b64 s[6:7], s[34:35]
	s_cbranch_execz .LBB0_1097
	v_lshlrev_b32_e32 v4, 16, v229
	s_branch .LBB0_1097

.LBB0_1272:
	s_bitcmp1_b32 s13, 0
	s_cselect_b32 s13, 0xc000, 0
	s_add_i32 s13, s13, 0
	s_add_i32 s15, s11, s13
	v_add_u32_e32 v96, s15, v75
	s_add_i32 s13, s10, s13
	v_add_u32_e32 v100, s13, v75
	ds_read_b128 v[76:79], v96
	ds_read_b128 v[84:87], v96 offset:1024
	ds_read_b128 v[92:95], v96 offset:2048
	ds_read_b128 v[96:99], v96 offset:3072
	ds_read_b128 v[80:83], v100 offset:16384
	ds_read_b128 v[88:91], v100 offset:17408
	ds_read_b128 v[198:201], v100 offset:18432
	ds_read_b128 v[202:205], v100 offset:19456
	ds_read_b128 v[206:209], v100 offset:20480
	ds_read_b128 v[210:213], v100 offset:21504
	s_waitcnt lgkmcnt(4)
	v_mfma_f32_16x16x32_bf16 v[64:67], v[92:95], v[80:83], v[64:67]
	s_add_u32 s0, s0, 0x80
	s_addc_u32 s1, s1, 0
	v_lshl_add_u64 v[70:71], v[70:71], 0, s[20:21]
	v_mfma_f32_16x16x32_bf16 v[48:51], v[76:79], v[80:83], v[48:51]
	v_lshl_add_u64 v[72:73], v[72:73], 0, s[20:21]
	s_cmpk_lg_i32 s0, 0x800
	s_mov_b32 s13, s14
	v_mfma_f32_16x16x32_bf16 v[48:51], v[84:87], v[88:91], v[48:51]
	v_mfma_f32_16x16x32_bf16 v[64:67], v[96:99], v[88:91], v[64:67]
	ds_read_b128 v[214:217], v100 offset:22528
	ds_read_b128 v[218:221], v100 offset:23552
	s_waitcnt lgkmcnt(4)
	v_mfma_f32_16x16x32_bf16 v[60:63], v[76:79], v[198:201], v[60:63]
	v_mfma_f32_16x16x32_bf16 v[56:59], v[92:95], v[198:201], v[56:59]
	v_mfma_f32_16x16x32_bf16 v[60:63], v[84:87], v[202:205], v[60:63]
	v_mfma_f32_16x16x32_bf16 v[56:59], v[96:99], v[202:205], v[56:59]
	ds_read_b128 v[80:83], v100 offset:32768
	ds_read_b128 v[88:91], v100 offset:33792
	s_waitcnt lgkmcnt(4)
	v_mfma_f32_16x16x32_bf16 v[44:47], v[76:79], v[206:209], v[44:47]
	v_mfma_f32_16x16x32_bf16 v[40:43], v[92:95], v[206:209], v[40:43]
	v_mfma_f32_16x16x32_bf16 v[44:47], v[84:87], v[210:213], v[44:47]
	v_mfma_f32_16x16x32_bf16 v[40:43], v[96:99], v[210:213], v[40:43]
	ds_read_b128 v[198:201], v100 offset:34816
	ds_read_b128 v[202:205], v100 offset:35840
	s_waitcnt lgkmcnt(4)
	v_mfma_f32_16x16x32_bf16 v[36:39], v[76:79], v[214:217], v[36:39]
	v_mfma_f32_16x16x32_bf16 v[32:35], v[92:95], v[214:217], v[32:35]
	v_mfma_f32_16x16x32_bf16 v[36:39], v[84:87], v[218:221], v[36:39]
	v_mfma_f32_16x16x32_bf16 v[32:35], v[96:99], v[218:221], v[32:35]
	ds_read_b128 v[206:209], v100 offset:36864
	ds_read_b128 v[210:213], v100 offset:37888
	s_waitcnt lgkmcnt(4)
	v_mfma_f32_16x16x32_bf16 v[28:31], v[76:79], v[80:83], v[28:31]
	v_mfma_f32_16x16x32_bf16 v[24:27], v[92:95], v[80:83], v[24:27]
	v_mfma_f32_16x16x32_bf16 v[28:31], v[84:87], v[88:91], v[28:31]
	v_mfma_f32_16x16x32_bf16 v[24:27], v[96:99], v[88:91], v[24:27]
	ds_read_b128 v[214:217], v100 offset:38912
	ds_read_b128 v[218:221], v100 offset:39936
	s_waitcnt lgkmcnt(4)
	v_mfma_f32_16x16x32_bf16 v[20:23], v[76:79], v[198:201], v[20:23]
	v_mfma_f32_16x16x32_bf16 v[8:11], v[92:95], v[198:201], v[8:11]
	v_mfma_f32_16x16x32_bf16 v[20:23], v[84:87], v[202:205], v[20:23]
	v_mfma_f32_16x16x32_bf16 v[8:11], v[96:99], v[202:205], v[8:11]
	s_waitcnt lgkmcnt(2)
	v_mfma_f32_16x16x32_bf16 v[16:19], v[76:79], v[206:209], v[16:19]
	v_mfma_f32_16x16x32_bf16 v[12:15], v[92:95], v[206:209], v[12:15]
	v_mfma_f32_16x16x32_bf16 v[16:19], v[84:87], v[210:213], v[16:19]
	v_mfma_f32_16x16x32_bf16 v[12:15], v[96:99], v[210:213], v[12:15]
	s_waitcnt vmcnt(0)
	s_waitcnt vmcnt(0) lgkmcnt(0)
	v_mfma_f32_16x16x32_bf16 v[4:7], v[76:79], v[214:217], v[4:7]
	s_barrier
	v_mfma_f32_16x16x32_bf16 v[0:3], v[92:95], v[214:217], v[0:3]
	v_mfma_f32_16x16x32_bf16 v[4:7], v[84:87], v[218:221], v[4:7]
	v_mfma_f32_16x16x32_bf16 v[0:3], v[96:99], v[218:221], v[0:3]
	s_cbranch_scc0 .LBB0_1275

.LBB0_1334:
	s_or_b64 exec, exec, s[10:11]
	s_waitcnt vmcnt(3)
	v_mov_b32_e32 v26, v21
	s_waitcnt vmcnt(2)
	v_mov_b32_e32 v27, v17
	v_mov_b32_e32 v24, v20
	v_mov_b32_e32 v25, v16
	v_pk_mul_f32 v[26:27], v[26:27], v[26:27]
	v_mov_b32_e32 v78, v22
	v_mov_b32_e32 v79, v18
	v_pk_fma_f32 v[24:25], v[24:25], v[24:25], v[26:27]
	v_mov_b32_e32 v80, v23
	v_pk_fma_f32 v[24:25], v[78:79], v[78:79], v[24:25]
	s_waitcnt vmcnt(1)
	v_mov_b32_e32 v78, v13
	s_waitcnt vmcnt(0)
	v_mov_b32_e32 v79, v9
	v_mov_b32_e32 v81, v19
	v_mov_b32_e32 v26, v12
	v_mov_b32_e32 v27, v8
	v_pk_mul_f32 v[78:79], v[78:79], v[78:79]
	v_pk_fma_f32 v[24:25], v[80:81], v[80:81], v[24:25]
	v_mov_b32_e32 v80, v14
	v_mov_b32_e32 v81, v10
	v_pk_fma_f32 v[26:27], v[26:27], v[26:27], v[78:79]
	v_mov_b32_e32 v82, v15
	v_mov_b32_e32 v83, v11
	v_pk_fma_f32 v[26:27], v[80:81], v[80:81], v[26:27]
	v_add_f32_e32 v24, v24, v25
	v_pk_fma_f32 v[26:27], v[82:83], v[82:83], v[26:27]
	s_nop 0
	v_add_f32_e32 v24, v24, v26
	v_add_f32_e32 v24, v24, v27
	ds_bpermute_b32 v25, v31, v24
	s_waitcnt lgkmcnt(0)
	v_add_f32_e32 v24, v24, v25
	ds_swizzle_b32 v25, v24 offset:swizzle(SWAP,16)
	s_waitcnt lgkmcnt(0)
	v_add_f32_e32 v24, v24, v25
	ds_swizzle_b32 v25, v24 offset:swizzle(SWAP,8)
	s_waitcnt lgkmcnt(0)
	v_add_f32_e32 v24, v24, v25
	ds_swizzle_b32 v25, v24 offset:swizzle(SWAP,4)
	s_waitcnt lgkmcnt(0)
	v_add_f32_e32 v24, v24, v25
	ds_swizzle_b32 v25, v24 offset:swizzle(SWAP,2)
	s_waitcnt lgkmcnt(0)
	v_add_f32_e32 v24, v24, v25
	ds_swizzle_b32 v25, v24 offset:swizzle(SWAP,1)
	s_waitcnt lgkmcnt(0)
	v_add_f32_e32 v24, v24, v25
	v_fmamk_f32 v24, v24, 0x3a800000, v189
	v_cmp_gt_f32_e64 s[34:35], s28, v24
	v_mul_f32_e32 v25, 0x4b800000, v24
	s_nop 0
	v_cndmask_b32_e64 v24, v24, v25, s[34:35]
	v_rsq_f32_e32 v24, v24
	s_nop 0
	v_mul_f32_e32 v25, 0x45800000, v24
	v_cndmask_b32_e64 v29, v24, v25, s[34:35]
	v_add_u32_e32 v24, 0xffffe000, v28
	v_lshrrev_b32_e32 v24, 12, v24
	v_add_u32_e32 v24, 1, v24
	v_cmp_lt_i32_e64 s[34:35], s48, v28
	v_mul_f32_e32 v20, v20, v29
	v_mul_f32_e32 v21, v21, v29
	v_cndmask_b32_e64 v24, 0, v24, s[34:35]
	v_add_u32_e32 v26, s86, v24
	v_mov_b64_e32 v[24:25], s[4:5]
	v_mad_u64_u32 v[78:79], s[6:7], v26, s50, v[24:25]
	v_lshl_add_u64 v[80:81], v[78:79], 0, s[58:59]
	v_lshl_add_u64 v[82:83], v[78:79], 0, v[164:165]
	v_lshl_add_u64 v[78:79], v[80:81], 0, v[164:165]
	v_mov_b32_e32 v252, v78
	v_mov_b32_e32 v253, v79
	global_load_dwordx4 v[198:201], v[32:33], off
	global_load_dwordx4 v[202:205], v[36:37], off
	global_load_dwordx4 v[206:209], v[40:41], off
	global_load_dwordx4 v[210:213], v[44:45], off
	global_load_dwordx4 v[214:217], v[82:83], off
	global_load_dwordx4 v[218:221], v[82:83], off offset:1024
	global_load_dwordx4 v[222:225], v[82:83], off offset:2048
	global_load_dwordx4 v[226:229], v[82:83], off offset:3072
	global_load_dwordx4 v[230:233], v[252:253], off
	global_load_dwordx4 v[240:243], v[252:253], off offset:1024
	global_load_dwordx4 v[244:247], v[252:253], off offset:2048
	global_load_dwordx4 v[248:251], v[252:253], off offset:3072
	s_waitcnt vmcnt(0)
	v_mov_b32_e32 v24, v198
	v_mov_b32_e32 v25, v199
	v_mov_b32_e32 v26, v200
	v_mov_b32_e32 v27, v201
	v_mov_b32_e32 v84, v214
	v_mov_b32_e32 v85, v215
	v_mov_b32_e32 v86, v216
	v_mov_b32_e32 v87, v217
	v_mov_b32_e32 v88, v230
	v_mov_b32_e32 v89, v231
	v_mov_b32_e32 v90, v232
	v_mov_b32_e32 v91, v233
	v_mul_f32_e32 v22, v22, v29
	v_mul_f32_e32 v23, v23, v29
	v_lshlrev_b32_e32 v78, 2, v34
	v_mov_b32_e32 v79, v165
	v_mul_f32_e32 v16, v16, v29
	v_mul_f32_e32 v17, v17, v29
	v_mul_f32_e32 v18, v18, v29
	v_mul_f32_e32 v19, v19, v29
	v_mul_f32_e32 v12, v12, v29
	v_mul_f32_e32 v13, v13, v29
	v_mul_f32_e32 v14, v14, v29
	v_mul_f32_e32 v15, v15, v29
	v_mul_f32_e32 v8, v8, v29
	v_mul_f32_e32 v9, v9, v29
	v_mul_f32_e32 v10, v10, v29
	v_mul_f32_e32 v11, v11, v29
	v_mul_f32_e32 v20, v24, v20
	v_mul_f32_e32 v21, v25, v21
	v_add_f32_e32 v24, 1.0, v88
	v_fma_f32 v20, v24, v20, v84
	v_add_f32_e32 v24, 1.0, v89
	v_fma_f32 v21, v24, v21, v85
	v_mul_f32_e32 v22, v26, v22
	v_add_f32_e32 v24, 1.0, v90
	v_fma_f32 v22, v22, v24, v86
	v_mul_f32_e32 v23, v27, v23
	v_add_f32_e32 v24, 1.0, v91
	v_fmac_f32_e32 v87, v23, v24
	v_cvt_pk_bf16_f32 v20, v20, v21
	v_cvt_pk_bf16_f32 v21, v22, v87
	global_store_dwordx2 v[48:49], v[20:21], off
	v_lshl_add_u64 v[84:85], v[80:81], 0, v[78:79]
	v_mov_b32_e32 v24, v202
	v_mov_b32_e32 v25, v203
	v_mov_b32_e32 v26, v204
	v_mov_b32_e32 v27, v205
	v_mov_b32_e32 v20, v218
	v_mov_b32_e32 v21, v219
	v_mov_b32_e32 v22, v220
	v_mov_b32_e32 v23, v221
	v_mul_f32_e32 v16, v16, v24
	v_mov_b32_e32 v84, v240
	v_mov_b32_e32 v85, v241
	v_mov_b32_e32 v86, v242
	v_mov_b32_e32 v87, v243
	v_mul_f32_e32 v17, v17, v25
	v_mul_f32_e32 v18, v18, v26
	v_mul_f32_e32 v19, v19, v27
	v_add_f32_e32 v24, 1.0, v84
	v_fma_f32 v16, v16, v24, v20
	v_add_f32_e32 v20, 1.0, v85
	v_fma_f32 v17, v17, v20, v21
	v_add_f32_e32 v20, 1.0, v86
	v_fma_f32 v18, v18, v20, v22
	v_add_f32_e32 v20, 1.0, v87
	v_fmac_f32_e32 v23, v19, v20
	v_lshlrev_b32_e32 v20, 2, v38
	v_mov_b32_e32 v21, v165
	v_cvt_pk_bf16_f32 v16, v16, v17
	v_cvt_pk_bf16_f32 v17, v18, v23
	global_store_dwordx2 v[48:49], v[16:17], off offset:512
	v_lshl_add_u64 v[26:27], v[80:81], 0, v[20:21]
	v_mov_b32_e32 v16, v206
	v_mov_b32_e32 v17, v207
	v_mov_b32_e32 v18, v208
	v_mov_b32_e32 v19, v209
	v_mov_b32_e32 v22, v222
	v_mov_b32_e32 v23, v223
	v_mov_b32_e32 v24, v224
	v_mov_b32_e32 v25, v225
	v_mov_b32_e32 v84, v244
	v_mov_b32_e32 v85, v245
	v_mov_b32_e32 v86, v246
	v_mov_b32_e32 v87, v247
	v_mul_f32_e32 v12, v12, v16
	v_mul_f32_e32 v13, v13, v17
	v_add_f32_e32 v16, 1.0, v84
	v_fma_f32 v12, v12, v16, v22
	v_add_f32_e32 v16, 1.0, v85
	v_fma_f32 v13, v13, v16, v23
	v_mul_f32_e32 v14, v14, v18
	v_add_f32_e32 v16, 1.0, v86
	v_fma_f32 v14, v14, v16, v24
	v_mul_f32_e32 v15, v15, v19
	v_add_f32_e32 v16, 1.0, v87
	v_fmac_f32_e32 v25, v15, v16
	v_lshlrev_b32_e32 v22, 2, v42
	v_mov_b32_e32 v23, v165
	v_cvt_pk_bf16_f32 v12, v12, v13
	v_cvt_pk_bf16_f32 v13, v14, v25
	global_store_dwordx2 v[48:49], v[12:13], off offset:1024
	v_lshl_add_u64 v[24:25], v[80:81], 0, v[22:23]
	v_mov_b32_e32 v16, v210
	v_mov_b32_e32 v17, v211
	v_mov_b32_e32 v18, v212
	v_mov_b32_e32 v19, v213
	v_mov_b32_e32 v12, v226
	v_mov_b32_e32 v13, v227
	v_mov_b32_e32 v14, v228
	v_mov_b32_e32 v15, v229
	v_mul_f32_e32 v8, v8, v16
	v_mov_b32_e32 v24, v248
	v_mov_b32_e32 v25, v249
	v_mov_b32_e32 v26, v250
	v_mov_b32_e32 v27, v251
	v_mul_f32_e32 v9, v9, v17
	v_mul_f32_e32 v10, v10, v18
	v_mul_f32_e32 v11, v11, v19
	v_add_f32_e32 v16, 1.0, v24
	v_fma_f32 v8, v8, v16, v12
	v_add_f32_e32 v12, 1.0, v25
	v_fma_f32 v9, v9, v12, v13
	v_add_f32_e32 v12, 1.0, v26
	v_fma_f32 v10, v10, v12, v14
	v_add_f32_e32 v12, 1.0, v27
	v_fmac_f32_e32 v15, v11, v12
	v_cvt_pk_bf16_f32 v8, v8, v9
	v_cvt_pk_bf16_f32 v9, v10, v15
	global_store_dwordx2 v[48:49], v[8:9], off offset:1536
	s_and_saveexec_b64 s[10:11], vcc
	s_cbranch_execz .LBB0_1331
	v_pk_mul_f32 v[8:9], v[76:77], v[76:77]
	v_pk_mul_f32 v[10:11], v[68:69], v[68:69]
	v_pk_fma_f32 v[8:9], v[74:75], v[74:75], v[8:9]
	v_pk_fma_f32 v[10:11], v[66:67], v[66:67], v[10:11]
	v_pk_fma_f32 v[8:9], v[72:73], v[72:73], v[8:9]
	v_pk_fma_f32 v[10:11], v[64:65], v[64:65], v[10:11]
	v_pk_fma_f32 v[8:9], v[70:71], v[70:71], v[8:9]
	v_pk_fma_f32 v[10:11], v[62:63], v[62:63], v[10:11]
	v_add_f32_e32 v8, v8, v9
	v_add_f32_e32 v8, v11, v8
	v_add_f32_e32 v8, v10, v8
	ds_bpermute_b32 v9, v31, v8
	v_lshlrev_b64 v[14:15], 11, v[60:61]
	s_waitcnt lgkmcnt(0)
	v_add_f32_e32 v8, v8, v9
	ds_swizzle_b32 v9, v8 offset:swizzle(SWAP,16)
	s_waitcnt lgkmcnt(0)
	v_add_f32_e32 v8, v8, v9
	ds_swizzle_b32 v9, v8 offset:swizzle(SWAP,8)
	s_waitcnt lgkmcnt(0)
	v_add_f32_e32 v8, v8, v9
	ds_swizzle_b32 v9, v8 offset:swizzle(SWAP,4)
	s_waitcnt lgkmcnt(0)
	v_add_f32_e32 v8, v8, v9
	ds_swizzle_b32 v9, v8 offset:swizzle(SWAP,2)
	s_waitcnt lgkmcnt(0)
	v_add_f32_e32 v8, v8, v9
	ds_swizzle_b32 v9, v8 offset:swizzle(SWAP,1)
	s_waitcnt lgkmcnt(0)
	v_add_f32_e32 v8, v8, v9
	v_fmamk_f32 v8, v8, 0x3a800000, v189
	v_cmp_gt_f32_e32 vcc, s28, v8
	v_mul_f32_e32 v9, 0x4b800000, v8
	s_nop 0
	v_cndmask_b32_e32 v8, v8, v9, vcc
	v_rsq_f32_e32 v8, v8
	s_nop 0
	v_mul_f32_e32 v9, 0x45800000, v8
	v_cndmask_b32_e32 v24, v8, v9, vcc
	v_add_u32_e32 v8, 0xffffe000, v60
	v_lshrrev_b32_e32 v8, 12, v8
	v_add_u32_e32 v8, 1, v8
	v_cmp_lt_i32_e32 vcc, s48, v60
	s_nop 1
	v_cndmask_b32_e32 v8, 0, v8, vcc
	v_add_u32_e32 v10, s86, v8
	v_mov_b64_e32 v[8:9], s[4:5]
	v_mad_u64_u32 v[8:9], s[6:7], v10, s50, v[8:9]
	v_lshl_add_u64 v[16:17], v[8:9], 0, s[58:59]
	v_lshl_add_u64 v[8:9], v[8:9], 0, v[164:165]
	v_lshl_add_u64 v[18:19], v[16:17], 0, v[164:165]
	v_mov_b32_e32 v254, v18
	v_mov_b32_e32 v255, v19
	global_load_dwordx4 v[214:217], v[8:9], off
	global_load_dwordx4 v[218:221], v[8:9], off offset:1024
	global_load_dwordx4 v[222:225], v[8:9], off offset:2048
	global_load_dwordx4 v[226:229], v[8:9], off offset:3072
	global_load_dwordx4 v[230:233], v[254:255], off
	global_load_dwordx4 v[240:243], v[254:255], off offset:1024
	global_load_dwordx4 v[244:247], v[254:255], off offset:2048
	global_load_dwordx4 v[248:251], v[254:255], off offset:3072
	s_waitcnt vmcnt(0)
	v_mov_b32_e32 v10, v198
	v_mov_b32_e32 v11, v199
	v_mov_b32_e32 v12, v200
	v_mov_b32_e32 v13, v201
	v_mov_b32_e32 v60, v214
	v_mov_b32_e32 v61, v215
	v_mov_b32_e32 v62, v216
	v_mov_b32_e32 v63, v217
	v_mov_b32_e32 v64, v230
	v_mov_b32_e32 v65, v231
	v_mov_b32_e32 v66, v232
	v_mov_b32_e32 v67, v233
	v_mul_f32_e32 v18, v5, v24
	v_mul_f32_e32 v10, v10, v18
	v_add_f32_e32 v18, 1.0, v64
	v_fma_f32 v10, v18, v10, v60
	v_mul_f32_e32 v18, v59, v24
	v_mul_f32_e32 v11, v11, v18
	v_add_f32_e32 v18, 1.0, v65
	v_fma_f32 v11, v18, v11, v61
	v_mul_f32_e32 v18, v7, v24
	v_mul_f32_e32 v12, v12, v18
	v_add_f32_e32 v18, 1.0, v66
	v_fma_f32 v12, v12, v18, v62
	v_mul_f32_e32 v18, v57, v24
	v_mul_f32_e32 v13, v13, v18
	v_add_f32_e32 v18, 1.0, v67
	v_fmac_f32_e32 v63, v13, v18
	v_lshl_add_u64 v[18:19], v[46:47], 0, v[14:15]
	v_cvt_pk_bf16_f32 v10, v10, v11
	v_cvt_pk_bf16_f32 v11, v12, v63
	global_store_dwordx2 v[18:19], v[10:11], off
	v_lshl_add_u64 v[14:15], v[16:17], 0, v[78:79]
	v_mov_b32_e32 v10, v202
	v_mov_b32_e32 v11, v203
	v_mov_b32_e32 v12, v204
	v_mov_b32_e32 v13, v205
	v_mov_b32_e32 v60, v218
	v_mov_b32_e32 v61, v219
	v_mov_b32_e32 v62, v220
	v_mov_b32_e32 v63, v221
	v_mov_b32_e32 v64, v240
	v_mov_b32_e32 v65, v241
	v_mov_b32_e32 v66, v242
	v_mov_b32_e32 v67, v243
	v_mul_f32_e32 v14, v4, v24
	v_mul_f32_e32 v10, v14, v10
	v_add_f32_e32 v14, 1.0, v64
	v_fma_f32 v10, v10, v14, v60
	v_mul_f32_e32 v14, v58, v24
	v_mul_f32_e32 v11, v14, v11
	v_add_f32_e32 v14, 1.0, v65
	v_fma_f32 v11, v11, v14, v61
	v_mul_f32_e32 v14, v6, v24
	v_mul_f32_e32 v12, v14, v12
	v_add_f32_e32 v14, 1.0, v66
	v_fma_f32 v12, v12, v14, v62
	v_mul_f32_e32 v14, v56, v24
	v_mul_f32_e32 v13, v14, v13
	v_add_f32_e32 v14, 1.0, v67
	v_fmac_f32_e32 v63, v13, v14
	v_cvt_pk_bf16_f32 v10, v10, v11
	v_cvt_pk_bf16_f32 v11, v12, v63
	global_store_dwordx2 v[18:19], v[10:11], off offset:512
	v_lshl_add_u64 v[14:15], v[16:17], 0, v[20:21]
	v_mov_b32_e32 v10, v206
	v_mov_b32_e32 v11, v207
	v_mov_b32_e32 v12, v208
	v_mov_b32_e32 v13, v209
	v_mov_b32_e32 v60, v222
	v_mov_b32_e32 v61, v223
	v_mov_b32_e32 v62, v224
	v_mov_b32_e32 v63, v225
	v_mov_b32_e32 v64, v244
	v_mov_b32_e32 v65, v245
	v_mov_b32_e32 v66, v246
	v_mov_b32_e32 v67, v247
	v_mul_f32_e32 v14, v1, v24
	v_lshl_add_u64 v[16:17], v[16:17], 0, v[22:23]
	v_mul_f32_e32 v10, v14, v10
	v_add_f32_e32 v14, 1.0, v64
	v_fma_f32 v10, v10, v14, v60
	v_mul_f32_e32 v14, v55, v24
	v_mul_f32_e32 v11, v14, v11
	v_add_f32_e32 v14, 1.0, v65
	v_fma_f32 v11, v11, v14, v61
	v_mul_f32_e32 v14, v3, v24
	v_mul_f32_e32 v12, v14, v12
	v_add_f32_e32 v14, 1.0, v66
	v_fma_f32 v12, v12, v14, v62
	v_mul_f32_e32 v14, v53, v24
	v_mul_f32_e32 v13, v14, v13
	v_add_f32_e32 v14, 1.0, v67
	v_fmac_f32_e32 v63, v13, v14
	v_cvt_pk_bf16_f32 v10, v10, v11
	v_cvt_pk_bf16_f32 v11, v12, v63
	global_store_dwordx2 v[18:19], v[10:11], off offset:1024
	v_mov_b32_e32 v12, v210
	v_mov_b32_e32 v13, v211
	v_mov_b32_e32 v14, v212
	v_mov_b32_e32 v15, v213
	s_nop 0
	v_mov_b32_e32 v8, v226
	v_mov_b32_e32 v9, v227
	v_mov_b32_e32 v10, v228
	v_mov_b32_e32 v11, v229
	s_nop 0
	v_mov_b32_e32 v20, v248
	v_mov_b32_e32 v21, v249
	v_mov_b32_e32 v22, v250
	v_mov_b32_e32 v23, v251
	v_mul_f32_e32 v16, v0, v24
	v_mul_f32_e32 v12, v16, v12
	v_add_f32_e32 v16, 1.0, v20
	v_fma_f32 v8, v12, v16, v8
	v_mul_f32_e32 v12, v54, v24
	v_mul_f32_e32 v12, v12, v13
	v_add_f32_e32 v13, 1.0, v21
	v_fma_f32 v9, v12, v13, v9
	v_mul_f32_e32 v12, v2, v24
	v_mul_f32_e32 v12, v12, v14
	v_add_f32_e32 v13, 1.0, v22
	v_fma_f32 v10, v12, v13, v10
	v_mul_f32_e32 v12, v52, v24
	v_mul_f32_e32 v12, v12, v15
	v_add_f32_e32 v13, 1.0, v23
	v_fmac_f32_e32 v11, v12, v13
	v_cvt_pk_bf16_f32 v8, v8, v9
	v_cvt_pk_bf16_f32 v9, v10, v11
	global_store_dwordx2 v[18:19], v[8:9], off offset:1536
	s_branch .LBB0_1331

.LBB0_1560:
	s_bitcmp1_b32 s7, 0
	s_cselect_b32 s7, 0xc000, 0
	s_add_i32 s7, s7, 0
	s_add_i32 s14, s11, s7
	v_add_u32_e32 v96, s14, v75
	s_add_i32 s7, s10, s7
	v_add_u32_e32 v100, s7, v75
	ds_read_b128 v[76:79], v96
	ds_read_b128 v[84:87], v96 offset:1024
	ds_read_b128 v[92:95], v96 offset:2048
	ds_read_b128 v[96:99], v96 offset:3072
	ds_read_b128 v[80:83], v100 offset:16384
	ds_read_b128 v[88:91], v100 offset:17408
	ds_read_b128 v[198:201], v100 offset:18432
	ds_read_b128 v[202:205], v100 offset:19456
	ds_read_b128 v[206:209], v100 offset:20480
	ds_read_b128 v[210:213], v100 offset:21504
	s_waitcnt lgkmcnt(4)
	v_mfma_f32_16x16x32_bf16 v[64:67], v[92:95], v[80:83], v[64:67]
	s_add_u32 s4, s4, 0x8000
	s_addc_u32 s5, s5, 0
	s_cmp_lg_u32 s4, 0x160000
	v_mfma_f32_16x16x32_bf16 v[32:35], v[76:79], v[80:83], v[32:35]
	s_mov_b32 s7, s13
	v_mfma_f32_16x16x32_bf16 v[32:35], v[84:87], v[88:91], v[32:35]
	v_mfma_f32_16x16x32_bf16 v[64:67], v[96:99], v[88:91], v[64:67]
	ds_read_b128 v[214:217], v100 offset:22528
	ds_read_b128 v[218:221], v100 offset:23552
	s_waitcnt lgkmcnt(4)
	v_mfma_f32_16x16x32_bf16 v[60:63], v[76:79], v[198:201], v[60:63]
	v_mfma_f32_16x16x32_bf16 v[56:59], v[92:95], v[198:201], v[56:59]
	v_mfma_f32_16x16x32_bf16 v[60:63], v[84:87], v[202:205], v[60:63]
	v_mfma_f32_16x16x32_bf16 v[56:59], v[96:99], v[202:205], v[56:59]
	ds_read_b128 v[80:83], v100 offset:32768
	ds_read_b128 v[88:91], v100 offset:33792
	s_waitcnt lgkmcnt(4)
	v_mfma_f32_16x16x32_bf16 v[52:55], v[76:79], v[206:209], v[52:55]
	v_mfma_f32_16x16x32_bf16 v[48:51], v[92:95], v[206:209], v[48:51]
	v_mfma_f32_16x16x32_bf16 v[52:55], v[84:87], v[210:213], v[52:55]
	v_mfma_f32_16x16x32_bf16 v[48:51], v[96:99], v[210:213], v[48:51]
	ds_read_b128 v[198:201], v100 offset:34816
	ds_read_b128 v[202:205], v100 offset:35840
	s_waitcnt lgkmcnt(4)
	v_mfma_f32_16x16x32_bf16 v[44:47], v[76:79], v[214:217], v[44:47]
	v_mfma_f32_16x16x32_bf16 v[40:43], v[92:95], v[214:217], v[40:43]
	v_mfma_f32_16x16x32_bf16 v[44:47], v[84:87], v[218:221], v[44:47]
	v_mfma_f32_16x16x32_bf16 v[40:43], v[96:99], v[218:221], v[40:43]
	ds_read_b128 v[206:209], v100 offset:36864
	ds_read_b128 v[210:213], v100 offset:37888
	s_waitcnt lgkmcnt(4)
	v_mfma_f32_16x16x32_bf16 v[28:31], v[76:79], v[80:83], v[28:31]
	v_mfma_f32_16x16x32_bf16 v[24:27], v[92:95], v[80:83], v[24:27]
	v_mfma_f32_16x16x32_bf16 v[28:31], v[84:87], v[88:91], v[28:31]
	v_mfma_f32_16x16x32_bf16 v[24:27], v[96:99], v[88:91], v[24:27]
	ds_read_b128 v[214:217], v100 offset:38912
	ds_read_b128 v[218:221], v100 offset:39936
	s_waitcnt lgkmcnt(4)
	v_mfma_f32_16x16x32_bf16 v[20:23], v[76:79], v[198:201], v[20:23]
	v_mfma_f32_16x16x32_bf16 v[8:11], v[92:95], v[198:201], v[8:11]
	v_mfma_f32_16x16x32_bf16 v[20:23], v[84:87], v[202:205], v[20:23]
	v_mfma_f32_16x16x32_bf16 v[8:11], v[96:99], v[202:205], v[8:11]
	s_waitcnt lgkmcnt(2)
	v_mfma_f32_16x16x32_bf16 v[16:19], v[76:79], v[206:209], v[16:19]
	v_mfma_f32_16x16x32_bf16 v[12:15], v[92:95], v[206:209], v[12:15]
	v_mfma_f32_16x16x32_bf16 v[16:19], v[84:87], v[210:213], v[16:19]
	v_mfma_f32_16x16x32_bf16 v[12:15], v[96:99], v[210:213], v[12:15]
	s_waitcnt vmcnt(0)
	s_waitcnt vmcnt(0) lgkmcnt(0)
	v_mfma_f32_16x16x32_bf16 v[4:7], v[76:79], v[214:217], v[4:7]
	s_barrier
	v_mfma_f32_16x16x32_bf16 v[0:3], v[92:95], v[214:217], v[0:3]
	v_mfma_f32_16x16x32_bf16 v[4:7], v[84:87], v[218:221], v[4:7]
	v_mfma_f32_16x16x32_bf16 v[0:3], v[96:99], v[218:221], v[0:3]
	s_cbranch_scc0 .LBB0_1563
